# adds phase-0 adaLN GEMV: all 16 weight-row loads of a trip issued at the top (hipcc had sunk them into four serialized 4-load groups), counted vmcnt waits + register copies
# speedup vs baseline: 1.0047x; 1.0047x over previous
; #define LAS __attribute__((address_space(3)))
; __device__ __forceinline__ void phase0(CArgs a, LAS unsigned char* lds, int tid, int lane, int wave, int G, int bx) {
;     ...
;             for (int kk = 0; kk < 128; kk += 16) {
;                 const int k = kb + kk; const float* wp = Wl + (size_t)(half * 1024 + k) * NMOD;
;                 f32x2 wv[16];
; #pragma unroll
;                 for (int i = 0; i < 16; ++i) wv[i] = __builtin_nontemporal_load((const f32x2*)(wp + (size_t)i * NMOD));
; #pragma unroll
;                 for (int q = 0; q < 4; ++q) {
; #pragma unroll
;                     for (int r = 0; r < NB; ++r) { const f32x4 s4 = *(const LAS f32x4*)(S + r * 1024 + k + 4 * q);
;                         acc[r] += wv[4 * q] * s4[0]; acc[r] += wv[4 * q + 1] * s4[1]; acc[r] += wv[4 * q + 2] * s4[2]; acc[r] += wv[4 * q + 3] * s4[3]; } }
.LBB0_843:
	s_mov_b32 s45, -1
	s_mov_b32 s44, 0xfff4c000
	v_lshl_add_u64 v[206:207], v[12:13], 0, s[44:45]
	global_load_dwordx2 v[220:221], v[206:207], off nt
	s_mov_b32 s44, 0xfff58000
	v_lshl_add_u64 v[206:207], v[12:13], 0, s[44:45]
	global_load_dwordx2 v[222:223], v[206:207], off nt
	s_mov_b32 s44, 0xfff64000
	v_lshl_add_u64 v[206:207], v[12:13], 0, s[44:45]
	global_load_dwordx2 v[224:225], v[206:207], off nt
	s_mov_b32 s44, 0xfff70000
	v_lshl_add_u64 v[206:207], v[12:13], 0, s[44:45]
	global_load_dwordx2 v[226:227], v[206:207], off nt
	s_mov_b32 s44, 0xfff7c000
	v_lshl_add_u64 v[206:207], v[12:13], 0, s[44:45]
	global_load_dwordx2 v[228:229], v[206:207], off nt
	s_mov_b32 s44, 0xfff88000
	v_lshl_add_u64 v[206:207], v[12:13], 0, s[44:45]
	global_load_dwordx2 v[230:231], v[206:207], off nt
	s_mov_b32 s44, 0xfff94000
	v_lshl_add_u64 v[206:207], v[12:13], 0, s[44:45]
	global_load_dwordx2 v[232:233], v[206:207], off nt
	s_mov_b32 s44, 0xfffa0000
	v_lshl_add_u64 v[206:207], v[12:13], 0, s[44:45]
	global_load_dwordx2 v[234:235], v[206:207], off nt
	s_mov_b32 s44, 0xfffac000
	v_lshl_add_u64 v[206:207], v[12:13], 0, s[44:45]
	global_load_dwordx2 v[236:237], v[206:207], off nt
	s_mov_b32 s44, 0xfffb8000
	v_lshl_add_u64 v[206:207], v[12:13], 0, s[44:45]
	global_load_dwordx2 v[238:239], v[206:207], off nt
	s_mov_b32 s44, 0xfffc4000
	v_lshl_add_u64 v[206:207], v[12:13], 0, s[44:45]
	global_load_dwordx2 v[240:241], v[206:207], off nt
	s_mov_b32 s44, 0xfffd0000
	v_lshl_add_u64 v[206:207], v[12:13], 0, s[44:45]
	global_load_dwordx2 v[242:243], v[206:207], off nt
	s_mov_b32 s44, 0xfffdc000
	v_lshl_add_u64 v[206:207], v[12:13], 0, s[44:45]
	global_load_dwordx2 v[244:245], v[206:207], off nt
	s_mov_b32 s44, 0xfffe8000
	v_lshl_add_u64 v[206:207], v[12:13], 0, s[44:45]
	global_load_dwordx2 v[246:247], v[206:207], off nt
	s_mov_b32 s44, 0xffff4000
	v_lshl_add_u64 v[206:207], v[12:13], 0, s[44:45]
	global_load_dwordx2 v[248:249], v[206:207], off nt
	global_load_dwordx2 v[250:251], v[12:13], off nt
	s_mov_b32 s6, 0xfff4c000
	v_add_co_u32_e32 v34, vcc, s6, v12
	s_mov_b32 s6, 0xfff58000
	s_nop 0
	v_addc_co_u32_e32 v35, vcc, -1, v13, vcc
	v_add_co_u32_e32 v42, vcc, s6, v12
	s_mov_b32 s6, 0xfff64000
	s_nop 0
	v_addc_co_u32_e32 v43, vcc, -1, v13, vcc
	v_add_co_u32_e32 v44, vcc, s6, v12
	s_mov_b32 s6, 0xfff70000
	s_nop 0
	v_addc_co_u32_e32 v45, vcc, -1, v13, vcc
	v_add_co_u32_e32 v46, vcc, s6, v12
	s_add_i32 s6, s3, 0xfffdefd0
	s_nop 0
	v_addc_co_u32_e32 v47, vcc, -1, v13, vcc
	s_nop 0
	s_add_i32 s7, s3, 0xfffdffd0
	s_add_i32 s8, s3, 0xfffe0fd0
	s_add_i32 s9, s3, 0xfffe1fd0
	s_add_i32 s14, s3, 0xfffe2fd0
	s_add_i32 s15, s3, 0xfffe3fd0
	s_add_i32 s16, s3, 0xfffe4fd0
	s_add_i32 s17, s3, 0xfffe5fd0
	v_mov_b32_e32 v42, s6
	v_mov_b32_e32 v46, s7
	v_mov_b32_e32 v50, s8
	v_mov_b32_e32 v54, s9
	v_mov_b32_e32 v58, s14
	v_mov_b32_e32 v62, s15
	v_mov_b32_e32 v66, s16
	v_mov_b32_e32 v70, s17
	ds_read_b128 v[42:45], v42
	ds_read_b128 v[46:49], v46
	ds_read_b128 v[50:53], v50
	ds_read_b128 v[54:57], v54
	ds_read_b128 v[58:61], v58
	ds_read_b128 v[62:65], v62
	ds_read_b128 v[66:69], v66
	ds_read_b128 v[70:73], v70
	s_add_i32 s18, s3, 0xfffe6fd0
	v_mov_b32_e32 v97, s18
	s_add_i32 s19, s3, 0xfffe7fd0
	s_waitcnt lgkmcnt(7)
	v_mov_b32_e32 v98, v45
	v_mov_b32_e32 v99, s19
	s_add_i32 s20, s3, 0xfffe8fd0
	s_waitcnt lgkmcnt(6)
	v_mov_b32_e32 v96, v49
	v_mov_b32_e32 v103, s20
	s_add_i32 s21, s3, 0xfffe9fd0
	s_waitcnt lgkmcnt(5)
	v_mov_b32_e32 v102, v53
	v_mov_b32_e32 v104, s21
	s_add_i32 s22, s3, 0xfffeafd0
	s_waitcnt lgkmcnt(4)
	v_mov_b32_e32 v112, v57
	s_add_i32 s23, s3, 0xfffebfd0
	v_mov_b32_e32 v105, s22
	v_mov_b32_e32 v106, s23
	s_waitcnt lgkmcnt(3)
	v_mov_b32_e32 v110, v61
	s_waitcnt lgkmcnt(2)
	v_mov_b32_e32 v118, v65
	s_add_i32 s24, s3, 0xfffecfd0
	v_mov_b32_e32 v107, s24
	s_add_i32 s25, s3, 0xfffedfd0
	s_add_i32 s26, s3, 0xfffeefd0
	s_add_i32 s27, s3, 0xfffeffd0
	v_mov_b32_e32 v111, s25
	v_mov_b32_e32 v113, s26
	v_mov_b32_e32 v119, s27
	s_waitcnt lgkmcnt(1)
	v_mov_b32_e32 v124, v69
	s_waitcnt lgkmcnt(0)
	v_mov_b32_e32 v122, v73
	s_add_i32 s28, s3, 0xffff0fd0
	s_add_i32 s29, s3, 0xffff1fd0
	v_mov_b32_e32 v123, s28
	v_mov_b32_e32 v125, s29
	s_add_i32 s30, s3, 0xffff2fd0
	s_add_i32 s31, s3, 0xffff3fd0
	v_mov_b32_e32 v131, s30
	v_mov_b32_e32 v154, s31
	s_add_i32 s6, s3, 0xffff4fd0
	s_add_i32 s7, s3, 0xffff5fd0
	s_add_i32 s8, s3, 0xfffe0fe0
	s_add_i32 s9, s3, 0xfffe1fe0
	s_add_i32 s31, s3, 0xffff3fe0
	s_add_i32 s14, s3, 0xfffe2fe0
	s_add_i32 s15, s3, 0xfffe3fe0
	s_add_i32 s16, s3, 0xfffe4fe0
	s_add_i32 s17, s3, 0xfffe5fe0
	s_add_i32 s18, s3, 0xfffe6fe0
	s_add_i32 s19, s3, 0xfffe7fe0
	s_add_i32 s20, s3, 0xfffe8fe0
	s_add_i32 s21, s3, 0xfffe9fe0
	s_add_i32 s22, s3, 0xfffeafe0
	s_add_i32 s23, s3, 0xfffebfe0
	s_add_i32 s24, s3, 0xfffecfe0
	s_add_i32 s25, s3, 0xfffedfe0
	s_add_i32 s26, s3, 0xfffeefe0
	s_add_i32 s27, s3, 0xfffeffe0
	s_add_i32 s28, s3, 0xffff0fe0
	s_add_i32 s29, s3, 0xffff1fe0
	s_add_i32 s30, s3, 0xffff2fe0
	s_add_i32 s33, s3, 0xffff5000
	s_add_i32 s34, s3, 0xffff6000
	s_waitcnt vmcnt(15)
	v_mov_b32_e32 v90, v220
	v_mov_b32_e32 v91, v221
	v_pk_fma_f32 v[88:89], v[90:91], v[42:43], v[88:89] op_sel_hi:[1,0,1]
	s_add_i32 s2, s2, 16
	s_waitcnt vmcnt(14)
	v_mov_b32_e32 v92, v222
	v_mov_b32_e32 v93, v223
	v_pk_fma_f32 v[42:43], v[92:93], v[42:43], v[88:89] op_sel:[0,1,0]
	s_waitcnt vmcnt(13)
	v_mov_b32_e32 v94, v224
	v_mov_b32_e32 v95, v225
	v_pk_fma_f32 v[88:89], v[94:95], v[44:45], v[42:43] op_sel_hi:[1,0,1]
	v_pk_fma_f32 v[42:43], v[90:91], v[46:47], v[86:87] op_sel_hi:[1,0,1]
	s_waitcnt vmcnt(12)
; #define LAS __attribute__((address_space(3)))
; __device__ __forceinline__ void phase0(CArgs a, LAS unsigned char* lds, int tid, int lane, int wave, int G, int bx) {
;     ...
;                 for (int i = 0; i < 16; ++i) wv[i] = __builtin_nontemporal_load((const f32x2*)(wp + (size_t)i * NMOD));
; #pragma unroll
;                 for (int q = 0; q < 4; ++q) {
; #pragma unroll
;                     for (int r = 0; r < NB; ++r) { const f32x4 s4 = *(const LAS f32x4*)(S + r * 1024 + k + 4 * q);
;                         acc[r] += wv[4 * q] * s4[0]; acc[r] += wv[4 * q + 1] * s4[1]; acc[r] += wv[4 * q + 2] * s4[2]; acc[r] += wv[4 * q + 3] * s4[3]; } }
	v_mov_b32_e32 v34, v226
	v_mov_b32_e32 v35, v227
	v_pk_fma_f32 v[156:157], v[34:35], v[98:99], v[88:89] op_sel_hi:[1,0,1]
	v_pk_fma_f32 v[42:43], v[92:93], v[46:47], v[42:43] op_sel:[0,1,0]
	v_pk_fma_f32 v[46:47], v[90:91], v[50:51], v[84:85] op_sel_hi:[1,0,1]
	v_pk_fma_f32 v[86:87], v[94:95], v[48:49], v[42:43] op_sel_hi:[1,0,1]
	ds_read_b128 v[42:45], v97
	v_pk_fma_f32 v[46:47], v[92:93], v[50:51], v[46:47] op_sel:[0,1,0]
	v_pk_fma_f32 v[50:51], v[90:91], v[54:55], v[82:83] op_sel_hi:[1,0,1]
	v_pk_fma_f32 v[100:101], v[94:95], v[52:53], v[46:47] op_sel_hi:[1,0,1]
	v_pk_fma_f32 v[50:51], v[92:93], v[54:55], v[50:51] op_sel:[0,1,0]
	ds_read_b128 v[46:49], v99
	v_pk_fma_f32 v[108:109], v[94:95], v[56:57], v[50:51] op_sel_hi:[1,0,1]
	v_pk_fma_f32 v[50:51], v[90:91], v[58:59], v[80:81] op_sel_hi:[1,0,1]
	v_pk_fma_f32 v[54:55], v[90:91], v[62:63], v[78:79] op_sel_hi:[1,0,1]
	v_pk_fma_f32 v[50:51], v[92:93], v[58:59], v[50:51] op_sel:[0,1,0]
	v_pk_fma_f32 v[58:59], v[90:91], v[66:67], v[76:77] op_sel_hi:[1,0,1]
	v_pk_fma_f32 v[114:115], v[94:95], v[60:61], v[50:51] op_sel_hi:[1,0,1]
	ds_read_b128 v[50:53], v103
	v_pk_fma_f32 v[54:55], v[92:93], v[62:63], v[54:55] op_sel:[0,1,0]
	v_pk_fma_f32 v[58:59], v[92:93], v[66:67], v[58:59] op_sel:[0,1,0]
	s_waitcnt lgkmcnt(2)
	v_pk_fma_f32 v[62:63], v[90:91], v[42:43], v[152:153] op_sel_hi:[1,0,1]
	v_pk_fma_f32 v[116:117], v[94:95], v[64:65], v[54:55] op_sel_hi:[1,0,1]
	ds_read_b128 v[54:57], v104
	v_pk_fma_f32 v[120:121], v[94:95], v[68:69], v[58:59] op_sel_hi:[1,0,1]
	v_pk_fma_f32 v[58:59], v[90:91], v[70:71], v[74:75] op_sel_hi:[1,0,1]
	v_pk_fma_f32 v[42:43], v[92:93], v[42:43], v[62:63] op_sel:[0,1,0]
	v_pk_fma_f32 v[58:59], v[92:93], v[70:71], v[58:59] op_sel:[0,1,0]
	v_pk_fma_f32 v[128:129], v[94:95], v[44:45], v[42:43] op_sel_hi:[1,0,1]
	s_waitcnt lgkmcnt(2)
	v_pk_fma_f32 v[42:43], v[90:91], v[46:47], v[150:151] op_sel_hi:[1,0,1]
	v_pk_fma_f32 v[126:127], v[94:95], v[72:73], v[58:59] op_sel_hi:[1,0,1]
	ds_read_b128 v[58:61], v105
	ds_read_b128 v[62:65], v106
	v_pk_fma_f32 v[42:43], v[92:93], v[46:47], v[42:43] op_sel:[0,1,0]
	s_waitcnt lgkmcnt(3)
	v_mov_b32_e32 v82, v53
	v_pk_fma_f32 v[104:105], v[94:95], v[48:49], v[42:43] op_sel_hi:[1,0,1]
	v_pk_fma_f32 v[42:43], v[90:91], v[50:51], v[148:149] op_sel_hi:[1,0,1]
	v_mov_b32_e32 v106, v49
	v_pk_fma_f32 v[42:43], v[92:93], v[50:51], v[42:43] op_sel:[0,1,0]
	s_waitcnt lgkmcnt(0)
	v_pk_fma_f32 v[48:49], v[90:91], v[62:63], v[142:143] op_sel_hi:[1,0,1]
	v_pk_fma_f32 v[84:85], v[94:95], v[52:53], v[42:43] op_sel_hi:[1,0,1]
	v_pk_fma_f32 v[42:43], v[90:91], v[54:55], v[146:147] op_sel_hi:[1,0,1]
	ds_read_b128 v[50:53], v107
	ds_read_b128 v[66:69], v111
	v_pk_fma_f32 v[42:43], v[92:93], v[54:55], v[42:43] op_sel:[0,1,0]
	v_mov_b32_e32 v130, v45
	v_pk_fma_f32 v[78:79], v[94:95], v[56:57], v[42:43] op_sel_hi:[1,0,1]
	v_pk_fma_f32 v[42:43], v[90:91], v[58:59], v[144:145] op_sel_hi:[1,0,1]
	v_mov_b32_e32 v46, v61
	v_pk_fma_f32 v[42:43], v[92:93], v[58:59], v[42:43] op_sel:[0,1,0]
	v_pk_fma_f32 v[48:49], v[92:93], v[62:63], v[48:49] op_sel:[0,1,0]
	v_pk_fma_f32 v[44:45], v[94:95], v[60:61], v[42:43] op_sel_hi:[1,0,1]
	ds_read_b128 v[60:63], v113
	ds_read_b128 v[70:73], v119
	s_waitcnt lgkmcnt(3)
	v_pk_fma_f32 v[54:55], v[90:91], v[50:51], v[140:141] op_sel_hi:[1,0,1]
	v_mov_b32_e32 v80, v57
	v_pk_fma_f32 v[50:51], v[92:93], v[50:51], v[54:55] op_sel:[0,1,0]
	v_mov_b32_e32 v54, v53
	v_pk_fma_f32 v[50:51], v[94:95], v[52:53], v[50:51] op_sel_hi:[1,0,1]
	s_waitcnt lgkmcnt(2)
	v_pk_fma_f32 v[52:53], v[90:91], v[66:67], v[134:135] op_sel_hi:[1,0,1]
	s_waitcnt lgkmcnt(1)
	v_pk_fma_f32 v[2:3], v[90:91], v[60:61], v[2:3] op_sel_hi:[1,0,1]
	s_waitcnt lgkmcnt(0)
	v_pk_fma_f32 v[0:1], v[90:91], v[70:71], v[0:1] op_sel_hi:[1,0,1]
	v_pk_fma_f32 v[52:53], v[92:93], v[66:67], v[52:53] op_sel:[0,1,0]
	v_pk_fma_f32 v[2:3], v[92:93], v[60:61], v[2:3] op_sel:[0,1,0]
	v_pk_fma_f32 v[0:1], v[92:93], v[70:71], v[0:1] op_sel:[0,1,0]
	v_pk_fma_f32 v[56:57], v[94:95], v[68:69], v[52:53] op_sel_hi:[1,0,1]
	v_mov_b32_e32 v52, v63
	v_pk_fma_f32 v[60:61], v[94:95], v[62:63], v[2:3] op_sel_hi:[1,0,1]
	ds_read_b128 v[74:77], v123
	v_pk_fma_f32 v[62:63], v[94:95], v[72:73], v[0:1] op_sel_hi:[1,0,1]
	ds_read_b128 v[0:3], v125
	v_mov_b32_e32 v42, v65
	v_pk_fma_f32 v[48:49], v[94:95], v[64:65], v[48:49] op_sel_hi:[1,0,1]
	v_mov_b32_e32 v66, v73
	s_waitcnt lgkmcnt(1)
	v_pk_fma_f32 v[64:65], v[90:91], v[74:75], v[138:139] op_sel_hi:[1,0,1]
	s_waitcnt lgkmcnt(0)
	v_pk_fma_f32 v[72:73], v[90:91], v[0:1], v[136:137] op_sel_hi:[1,0,1]
	v_pk_fma_f32 v[64:65], v[92:93], v[74:75], v[64:65] op_sel:[0,1,0]
	v_pk_fma_f32 v[0:1], v[92:93], v[0:1], v[72:73] op_sel:[0,1,0]
	v_mov_b32_e32 v58, v69
	v_pk_fma_f32 v[68:69], v[94:95], v[76:77], v[64:65] op_sel_hi:[1,0,1]
	v_mov_b32_e32 v70, v77
	v_mov_b32_e32 v64, v3
	v_pk_fma_f32 v[72:73], v[94:95], v[2:3], v[0:1] op_sel_hi:[1,0,1]
	ds_read_b128 v[74:77], v131
	ds_read_b128 v[0:3], v154
	v_pk_fma_f32 v[174:175], v[34:35], v[42:43], v[48:49] op_sel_hi:[1,0,1]
	v_mov_b32_e32 v42, s8
	v_pk_fma_f32 v[98:99], v[34:35], v[124:125], v[120:121] op_sel_hi:[1,0,1]
	s_waitcnt lgkmcnt(1)
	v_pk_fma_f32 v[132:133], v[90:91], v[74:75], v[132:133] op_sel_hi:[1,0,1]
	s_waitcnt lgkmcnt(0)
	v_pk_fma_f32 v[40:41], v[90:91], v[0:1], v[40:41] op_sel_hi:[1,0,1]
	v_pk_fma_f32 v[74:75], v[92:93], v[74:75], v[132:133] op_sel:[0,1,0]
	v_pk_fma_f32 v[0:1], v[92:93], v[0:1], v[40:41] op_sel:[0,1,0]
	v_mov_b32_e32 v40, s7
	v_pk_fma_f32 v[0:1], v[94:95], v[2:3], v[0:1] op_sel_hi:[1,0,1]
	v_mov_b32_e32 v2, v3
	v_mov_b32_e32 v3, s6
	ds_read_b128 v[132:135], v3
	ds_read_b128 v[136:139], v40
	s_add_i32 s6, s3, 0xffff6fd0
	s_add_i32 s7, s3, 0xffff7fd0
	v_mov_b32_e32 v3, s6
	s_waitcnt lgkmcnt(1)
; #define LAS __attribute__((address_space(3)))
; __device__ __forceinline__ void phase0(CArgs a, LAS unsigned char* lds, int tid, int lane, int wave, int G, int bx) {
;     ...
;                 for (int i = 0; i < 16; ++i) wv[i] = __builtin_nontemporal_load((const f32x2*)(wp + (size_t)i * NMOD));
; #pragma unroll
;                 for (int q = 0; q < 4; ++q) {
; #pragma unroll
;                     for (int r = 0; r < NB; ++r) { const f32x4 s4 = *(const LAS f32x4*)(S + r * 1024 + k + 4 * q);
;                         acc[r] += wv[4 * q] * s4[0]; acc[r] += wv[4 * q + 1] * s4[1]; acc[r] += wv[4 * q + 2] * s4[2]; acc[r] += wv[4 * q + 3] * s4[3]; } }
	v_pk_fma_f32 v[38:39], v[90:91], v[132:133], v[38:39] op_sel_hi:[1,0,1]
	s_waitcnt lgkmcnt(0)
	v_pk_fma_f32 v[36:37], v[90:91], v[136:137], v[36:37] op_sel_hi:[1,0,1]
	v_pk_fma_f32 v[38:39], v[92:93], v[132:133], v[38:39] op_sel:[0,1,0]
	v_pk_fma_f32 v[36:37], v[92:93], v[136:137], v[36:37] op_sel:[0,1,0]
	v_pk_fma_f32 v[38:39], v[94:95], v[134:135], v[38:39] op_sel_hi:[1,0,1]
	v_mov_b32_e32 v40, v135
	v_pk_fma_f32 v[36:37], v[94:95], v[138:139], v[36:37] op_sel_hi:[1,0,1]
	v_mov_b32_e32 v132, v139
	v_mov_b32_e32 v41, s7
	ds_read_b128 v[134:137], v3
	ds_read_b128 v[138:141], v41
	s_add_i32 s6, s3, 0xffff8fd0
	s_add_i32 s7, s3, 0xffff9fd0
	v_mov_b32_e32 v3, s6
	s_waitcnt lgkmcnt(1)
	v_pk_fma_f32 v[32:33], v[90:91], v[134:135], v[32:33] op_sel_hi:[1,0,1]
	s_waitcnt lgkmcnt(0)
	v_pk_fma_f32 v[30:31], v[90:91], v[138:139], v[30:31] op_sel_hi:[1,0,1]
	v_pk_fma_f32 v[32:33], v[92:93], v[134:135], v[32:33] op_sel:[0,1,0]
	v_pk_fma_f32 v[30:31], v[92:93], v[138:139], v[30:31] op_sel:[0,1,0]
	v_pk_fma_f32 v[32:33], v[94:95], v[136:137], v[32:33] op_sel_hi:[1,0,1]
	v_pk_fma_f32 v[30:31], v[94:95], v[140:141], v[30:31] op_sel_hi:[1,0,1]
	v_mov_b32_e32 v136, v141
	v_mov_b32_e32 v41, s7
	ds_read_b128 v[138:141], v3
	ds_read_b128 v[142:145], v41
	s_add_i32 s6, s3, 0xffffafd0
	s_add_i32 s7, s3, 0xffffbfd0
	v_mov_b32_e32 v3, s6
	s_waitcnt lgkmcnt(1)
	v_pk_fma_f32 v[28:29], v[90:91], v[138:139], v[28:29] op_sel_hi:[1,0,1]
	s_waitcnt lgkmcnt(0)
	v_pk_fma_f32 v[26:27], v[90:91], v[142:143], v[26:27] op_sel_hi:[1,0,1]
	v_pk_fma_f32 v[28:29], v[92:93], v[138:139], v[28:29] op_sel:[0,1,0]
	v_pk_fma_f32 v[26:27], v[92:93], v[142:143], v[26:27] op_sel:[0,1,0]
	v_pk_fma_f32 v[28:29], v[94:95], v[140:141], v[28:29] op_sel_hi:[1,0,1]
	v_pk_fma_f32 v[26:27], v[94:95], v[144:145], v[26:27] op_sel_hi:[1,0,1]
	v_mov_b32_e32 v140, v145
	v_mov_b32_e32 v41, s7
	ds_read_b128 v[142:145], v3
	ds_read_b128 v[146:149], v41
	s_add_i32 s6, s3, 0xffffcfd0
	s_add_i32 s7, s3, 0xffffdfd0
	v_mov_b32_e32 v3, s6
	s_waitcnt lgkmcnt(1)
	v_pk_fma_f32 v[24:25], v[90:91], v[142:143], v[24:25] op_sel_hi:[1,0,1]
	s_waitcnt lgkmcnt(0)
	v_pk_fma_f32 v[22:23], v[90:91], v[146:147], v[22:23] op_sel_hi:[1,0,1]
	v_pk_fma_f32 v[24:25], v[92:93], v[142:143], v[24:25] op_sel:[0,1,0]
	v_pk_fma_f32 v[22:23], v[92:93], v[146:147], v[22:23] op_sel:[0,1,0]
	v_pk_fma_f32 v[24:25], v[94:95], v[144:145], v[24:25] op_sel_hi:[1,0,1]
	v_pk_fma_f32 v[22:23], v[94:95], v[148:149], v[22:23] op_sel_hi:[1,0,1]
	v_mov_b32_e32 v144, v149
	v_mov_b32_e32 v41, s7
	ds_read_b128 v[146:149], v3
	ds_read_b128 v[150:153], v41
	s_add_i32 s6, s3, 0xffffefd0
	s_sub_i32 s7, s3, 48
	v_mov_b32_e32 v3, s6
	s_waitcnt lgkmcnt(1)
	v_pk_fma_f32 v[20:21], v[90:91], v[146:147], v[20:21] op_sel_hi:[1,0,1]
	s_waitcnt lgkmcnt(0)
	v_pk_fma_f32 v[18:19], v[90:91], v[150:151], v[18:19] op_sel_hi:[1,0,1]
	v_pk_fma_f32 v[20:21], v[92:93], v[146:147], v[20:21] op_sel:[0,1,0]
	v_pk_fma_f32 v[18:19], v[92:93], v[150:151], v[18:19] op_sel:[0,1,0]
	v_pk_fma_f32 v[20:21], v[94:95], v[148:149], v[20:21] op_sel_hi:[1,0,1]
	v_pk_fma_f32 v[18:19], v[94:95], v[152:153], v[18:19] op_sel_hi:[1,0,1]
	v_mov_b32_e32 v148, v153
	v_mov_b32_e32 v41, s7
	ds_read_b128 v[152:155], v3
	ds_read_b128 v[168:171], v41
	s_mov_b32 s6, 0xfff7c000
	v_mov_b32_e32 v138, v141
	s_add_i32 s7, s3, 0xfffdffe0
	s_waitcnt lgkmcnt(1)
	v_pk_fma_f32 v[16:17], v[90:91], v[152:153], v[16:17] op_sel_hi:[1,0,1]
	s_waitcnt lgkmcnt(0)
	v_pk_fma_f32 v[14:15], v[90:91], v[168:169], v[14:15] op_sel_hi:[1,0,1]
	v_pk_fma_f32 v[90:91], v[34:35], v[96:97], v[86:87] op_sel_hi:[1,0,1]
	v_pk_fma_f32 v[14:15], v[92:93], v[168:169], v[14:15] op_sel:[0,1,0]
	v_pk_fma_f32 v[168:169], v[34:35], v[82:83], v[84:85] op_sel_hi:[1,0,1]
	v_pk_fma_f32 v[158:159], v[94:95], v[170:171], v[14:15] op_sel_hi:[1,0,1]
	v_add_co_u32_e32 v14, vcc, s6, v12
	s_mov_b32 s6, 0xfff88000
	s_nop 0
	v_addc_co_u32_e32 v15, vcc, -1, v13, vcc
	v_add_co_u32_e32 v96, vcc, s6, v12
	s_mov_b32 s6, 0xfff94000
	s_nop 0
	v_addc_co_u32_e32 v97, vcc, -1, v13, vcc
	v_add_co_u32_e32 v82, vcc, s6, v12
	s_mov_b32 s6, 0xfffa0000
	s_nop 0
	v_addc_co_u32_e32 v83, vcc, -1, v13, vcc
	v_add_co_u32_e32 v84, vcc, s6, v12
	v_mov_b32_e32 v160, v171
	v_pk_fma_f32 v[170:171], v[34:35], v[80:81], v[78:79] op_sel_hi:[1,0,1]
	v_addc_co_u32_e32 v85, vcc, -1, v13, vcc
	s_nop 0
	s_nop 0
	s_add_i32 s6, s3, 0xfffdefe0
	v_pk_fma_f32 v[16:17], v[92:93], v[152:153], v[16:17] op_sel:[0,1,0]
	v_mov_b32_e32 v3, s6
	v_pk_fma_f32 v[152:153], v[94:95], v[154:155], v[16:17] op_sel_hi:[1,0,1]
	v_pk_fma_f32 v[16:17], v[34:35], v[130:131], v[128:129] op_sel_hi:[1,0,1]
	v_pk_fma_f32 v[130:131], v[34:35], v[2:3], v[0:1] op_sel_hi:[1,0,1]
	ds_read_b128 v[0:3], v3
	v_pk_fma_f32 v[74:75], v[94:95], v[76:77], v[74:75] op_sel_hi:[1,0,1]
	v_mov_b32_e32 v134, v137
	v_pk_fma_f32 v[94:95], v[34:35], v[118:119], v[116:117] op_sel_hi:[1,0,1]
	v_mov_b32_e32 v41, s7
	v_pk_fma_f32 v[120:121], v[34:35], v[138:139], v[28:29] op_sel_hi:[1,0,1]
	v_pk_fma_f32 v[118:119], v[34:35], v[140:141], v[26:27] op_sel_hi:[1,0,1]
	ds_read_b128 v[26:29], v42
	v_pk_fma_f32 v[86:87], v[34:35], v[112:113], v[108:109] op_sel_hi:[1,0,1]
	v_pk_fma_f32 v[108:109], v[34:35], v[122:123], v[126:127] op_sel_hi:[1,0,1]
	v_mov_b32_e32 v43, s9
	v_mov_b32_e32 v133, s31
	v_pk_fma_f32 v[124:125], v[34:35], v[134:135], v[32:33] op_sel_hi:[1,0,1]
	v_pk_fma_f32 v[122:123], v[34:35], v[136:137], v[30:31] op_sel_hi:[1,0,1]
	ds_read_b128 v[30:33], v41
	v_pk_fma_f32 v[128:129], v[34:35], v[40:41], v[38:39] op_sel_hi:[1,0,1]
	v_pk_fma_f32 v[126:127], v[34:35], v[132:133], v[36:37] op_sel_hi:[1,0,1]
	ds_read_b128 v[36:39], v43
	v_mov_b32_e32 v146, v149
	v_pk_fma_f32 v[172:173], v[34:35], v[46:47], v[44:45] op_sel_hi:[1,0,1]
	v_mov_b32_e32 v44, s14
	v_pk_fma_f32 v[88:89], v[34:35], v[102:103], v[100:101] op_sel_hi:[1,0,1]
	v_pk_fma_f32 v[92:93], v[34:35], v[110:111], v[114:115] op_sel_hi:[1,0,1]
	v_pk_fma_f32 v[114:115], v[34:35], v[144:145], v[22:23] op_sel_hi:[1,0,1]
	v_pk_fma_f32 v[112:113], v[34:35], v[146:147], v[20:21] op_sel_hi:[1,0,1]
	ds_read_b128 v[20:23], v44
	v_pk_fma_f32 v[110:111], v[34:35], v[148:149], v[18:19] op_sel_hi:[1,0,1]
	v_mov_b32_e32 v45, s15
	v_pk_fma_f32 v[184:185], v[34:35], v[66:67], v[62:63] op_sel_hi:[1,0,1]
	ds_read_b128 v[40:43], v45
	v_mov_b32_e32 v46, s16
	v_mov_b32_e32 v48, s17
	v_pk_fma_f32 v[182:183], v[34:35], v[52:53], v[60:61] op_sel_hi:[1,0,1]
	v_mov_b32_e32 v52, s18
	v_pk_fma_f32 v[188:189], v[34:35], v[64:65], v[72:73] op_sel_hi:[1,0,1]
	v_mov_b32_e32 v142, v145
	v_pk_fma_f32 v[176:177], v[34:35], v[54:55], v[50:51] op_sel_hi:[1,0,1]
	v_mov_b32_e32 v53, s19
	v_pk_fma_f32 v[186:187], v[34:35], v[70:71], v[68:69] op_sel_hi:[1,0,1]
	ds_read_b128 v[44:47], v46
	ds_read_b128 v[48:51], v48
	s_waitcnt lgkmcnt(7)
; #define LAS __attribute__((address_space(3)))
; __device__ __forceinline__ void phase0(CArgs a, LAS unsigned char* lds, int tid, int lane, int wave, int G, int bx) {
;     ...
;                 for (int i = 0; i < 16; ++i) wv[i] = __builtin_nontemporal_load((const f32x2*)(wp + (size_t)i * NMOD));
; #pragma unroll
;                 for (int q = 0; q < 4; ++q) {
; #pragma unroll
;                     for (int r = 0; r < NB; ++r) { const f32x4 s4 = *(const LAS f32x4*)(S + r * 1024 + k + 4 * q);
;                         acc[r] += wv[4 * q] * s4[0]; acc[r] += wv[4 * q + 1] * s4[1]; acc[r] += wv[4 * q + 2] * s4[2]; acc[r] += wv[4 * q + 3] * s4[3]; } }
	v_mov_b32_e32 v66, v3
	v_pk_fma_f32 v[116:117], v[34:35], v[142:143], v[24:25] op_sel_hi:[1,0,1]
	v_mov_b32_e32 v54, s20
	v_mov_b32_e32 v76, v77
	v_mov_b32_e32 v55, s21
	v_pk_fma_f32 v[150:151], v[34:35], v[106:107], v[104:105] op_sel_hi:[1,0,1]
	v_pk_fma_f32 v[190:191], v[34:35], v[76:77], v[74:75] op_sel_hi:[1,0,1]
	s_waitcnt lgkmcnt(6)
	v_mov_b32_e32 v74, v29
	v_mov_b32_e32 v154, v155
	v_pk_fma_f32 v[180:181], v[34:35], v[58:59], v[56:57] op_sel_hi:[1,0,1]
	v_mov_b32_e32 v56, s22
	v_mov_b32_e32 v57, s23
	v_pk_fma_f32 v[68:69], v[34:35], v[154:155], v[152:153] op_sel_hi:[1,0,1]
	v_pk_fma_f32 v[60:61], v[34:35], v[160:161], v[158:159] op_sel_hi:[1,0,1]
	s_waitcnt lgkmcnt(5)
	v_mov_b32_e32 v64, v33
	v_mov_b32_e32 v65, s24
	v_mov_b32_e32 v67, s25
	v_mov_b32_e32 v75, s26
	v_mov_b32_e32 v85, s27
	s_waitcnt lgkmcnt(2)
	v_mov_b32_e32 v96, v43
	v_mov_b32_e32 v97, s28
	v_mov_b32_e32 v101, s29
	s_waitcnt lgkmcnt(1)
	v_mov_b32_e32 v102, v47
	v_mov_b32_e32 v103, s30
	s_waitcnt lgkmcnt(0)
	v_mov_b32_e32 v100, v51
	s_add_i32 s6, s3, 0xffff4fe0
	s_add_i32 s7, s3, 0xffff5fe0
	s_add_i32 s8, s3, 0xfffe0ff0
	s_add_i32 s9, s3, 0xfffe1ff0
	s_add_i32 s14, s3, 0xfffe2ff0
	s_waitcnt vmcnt(11)
	v_mov_b32_e32 v78, v228
	v_mov_b32_e32 v79, v229
	v_pk_fma_f32 v[18:19], v[78:79], v[0:1], v[156:157] op_sel_hi:[1,0,1]
	s_add_i32 s15, s3, 0xfffe3ff0
	s_waitcnt vmcnt(10)
	v_mov_b32_e32 v80, v230
	v_mov_b32_e32 v81, v231
	v_pk_fma_f32 v[0:1], v[80:81], v[0:1], v[18:19] op_sel:[0,1,0]
	v_pk_fma_f32 v[18:19], v[78:79], v[26:27], v[88:89] op_sel_hi:[1,0,1]
	s_waitcnt vmcnt(9)
	v_mov_b32_e32 v82, v232
	v_mov_b32_e32 v83, v233
	v_pk_fma_f32 v[62:63], v[82:83], v[2:3], v[0:1] op_sel_hi:[1,0,1]
	v_pk_fma_f32 v[0:1], v[78:79], v[30:31], v[90:91] op_sel_hi:[1,0,1]
	v_pk_fma_f32 v[18:19], v[80:81], v[26:27], v[18:19] op_sel:[0,1,0]
	v_pk_fma_f32 v[0:1], v[80:81], v[30:31], v[0:1] op_sel:[0,1,0]
	v_pk_fma_f32 v[72:73], v[82:83], v[28:29], v[18:19] op_sel_hi:[1,0,1]
	v_pk_fma_f32 v[18:19], v[78:79], v[36:37], v[86:87] op_sel_hi:[1,0,1]
	v_pk_fma_f32 v[70:71], v[82:83], v[32:33], v[0:1] op_sel_hi:[1,0,1]
	ds_read_b128 v[0:3], v52
	ds_read_b128 v[24:27], v53
	v_pk_fma_f32 v[18:19], v[80:81], v[36:37], v[18:19] op_sel:[0,1,0]
	v_mov_b32_e32 v88, v23
	v_pk_fma_f32 v[86:87], v[82:83], v[38:39], v[18:19] op_sel_hi:[1,0,1]
	v_pk_fma_f32 v[18:19], v[78:79], v[20:21], v[92:93] op_sel_hi:[1,0,1]
	ds_read_b128 v[28:31], v55
	v_pk_fma_f32 v[18:19], v[80:81], v[20:21], v[18:19] op_sel:[0,1,0]
	s_waitcnt lgkmcnt(2)
	v_pk_fma_f32 v[16:17], v[78:79], v[0:1], v[16:17] op_sel_hi:[1,0,1]
	v_pk_fma_f32 v[92:93], v[82:83], v[22:23], v[18:19] op_sel_hi:[1,0,1]
	ds_read_b128 v[18:21], v54
	v_pk_fma_f32 v[22:23], v[78:79], v[40:41], v[94:95] op_sel_hi:[1,0,1]
	v_pk_fma_f32 v[0:1], v[80:81], v[0:1], v[16:17] op_sel:[0,1,0]
	v_pk_fma_f32 v[22:23], v[80:81], v[40:41], v[22:23] op_sel:[0,1,0]
	s_waitcnt lgkmcnt(2)
	v_pk_fma_f32 v[16:17], v[78:79], v[24:25], v[150:151] op_sel_hi:[1,0,1]
	v_pk_fma_f32 v[94:95], v[82:83], v[42:43], v[22:23] op_sel_hi:[1,0,1]
	v_pk_fma_f32 v[22:23], v[78:79], v[44:45], v[98:99] op_sel_hi:[1,0,1]
	ds_read_b128 v[32:35], v56
	v_pk_fma_f32 v[22:23], v[80:81], v[44:45], v[22:23] op_sel:[0,1,0]
	v_pk_fma_f32 v[106:107], v[82:83], v[2:3], v[0:1] op_sel_hi:[1,0,1]
	v_pk_fma_f32 v[98:99], v[82:83], v[46:47], v[22:23] op_sel_hi:[1,0,1]
	v_pk_fma_f32 v[22:23], v[78:79], v[48:49], v[108:109] op_sel_hi:[1,0,1]
	v_mov_b32_e32 v108, v3
	ds_read_b128 v[0:3], v57
	v_pk_fma_f32 v[16:17], v[80:81], v[24:25], v[16:17] op_sel:[0,1,0]
	v_pk_fma_f32 v[22:23], v[80:81], v[48:49], v[22:23] op_sel:[0,1,0]
	v_pk_fma_f32 v[76:77], v[82:83], v[26:27], v[16:17] op_sel_hi:[1,0,1]
	s_waitcnt lgkmcnt(2)
	v_pk_fma_f32 v[16:17], v[78:79], v[18:19], v[168:169] op_sel_hi:[1,0,1]
	v_pk_fma_f32 v[104:105], v[82:83], v[50:51], v[22:23] op_sel_hi:[1,0,1]
	v_pk_fma_f32 v[16:17], v[80:81], v[18:19], v[16:17] op_sel:[0,1,0]
	v_mov_b32_e32 v84, v27
	v_pk_fma_f32 v[58:59], v[82:83], v[20:21], v[16:17] op_sel_hi:[1,0,1]
	v_pk_fma_f32 v[16:17], v[78:79], v[28:29], v[170:171] op_sel_hi:[1,0,1]
	ds_read_b128 v[24:27], v65
	v_pk_fma_f32 v[16:17], v[80:81], v[28:29], v[16:17] op_sel:[0,1,0]
	s_waitcnt lgkmcnt(1)
	v_pk_fma_f32 v[22:23], v[78:79], v[0:1], v[174:175] op_sel_hi:[1,0,1]
	v_pk_fma_f32 v[52:53], v[82:83], v[30:31], v[16:17] op_sel_hi:[1,0,1]
	v_pk_fma_f32 v[16:17], v[78:79], v[32:33], v[172:173] op_sel_hi:[1,0,1]
	v_pk_fma_f32 v[0:1], v[80:81], v[0:1], v[22:23] op_sel:[0,1,0]
	v_pk_fma_f32 v[16:17], v[80:81], v[32:33], v[16:17] op_sel:[0,1,0]
	v_mov_b32_e32 v90, v39
	ds_read_b128 v[36:39], v67
	v_pk_fma_f32 v[18:19], v[82:83], v[34:35], v[16:17] op_sel_hi:[1,0,1]
	v_mov_b32_e32 v16, v3
	v_pk_fma_f32 v[22:23], v[82:83], v[2:3], v[0:1] op_sel_hi:[1,0,1]
	ds_read_b128 v[0:3], v75
	ds_read_b128 v[40:43], v85
	s_waitcnt lgkmcnt(3)
	v_pk_fma_f32 v[28:29], v[78:79], v[24:25], v[176:177] op_sel_hi:[1,0,1]
	v_mov_b32_e32 v20, v35
	v_pk_fma_f32 v[24:25], v[80:81], v[24:25], v[28:29] op_sel:[0,1,0]
	v_mov_b32_e32 v28, v27
	v_pk_fma_f32 v[24:25], v[82:83], v[26:27], v[24:25] op_sel_hi:[1,0,1]
	s_waitcnt lgkmcnt(2)
	v_pk_fma_f32 v[26:27], v[78:79], v[36:37], v[180:181] op_sel_hi:[1,0,1]
	s_waitcnt lgkmcnt(1)
	v_pk_fma_f32 v[34:35], v[78:79], v[0:1], v[182:183] op_sel_hi:[1,0,1]
	v_pk_fma_f32 v[26:27], v[80:81], v[36:37], v[26:27] op_sel:[0,1,0]
	v_pk_fma_f32 v[0:1], v[80:81], v[0:1], v[34:35] op_sel:[0,1,0]
	v_mov_b32_e32 v54, v31
	v_pk_fma_f32 v[30:31], v[82:83], v[38:39], v[26:27] op_sel_hi:[1,0,1]
	v_mov_b32_e32 v26, v3
	v_pk_fma_f32 v[34:35], v[82:83], v[2:3], v[0:1] op_sel_hi:[1,0,1]
	ds_read_b128 v[0:3], v97
	ds_read_b128 v[46:49], v101
	v_mov_b32_e32 v32, v39
	s_waitcnt lgkmcnt(2)
; #define LAS __attribute__((address_space(3)))
; __device__ __forceinline__ void phase0(CArgs a, LAS unsigned char* lds, int tid, int lane, int wave, int G, int bx) {
;     ...
;                 for (int i = 0; i < 16; ++i) wv[i] = __builtin_nontemporal_load((const f32x2*)(wp + (size_t)i * NMOD));
; #pragma unroll
;                 for (int q = 0; q < 4; ++q) {
; #pragma unroll
;                     for (int r = 0; r < NB; ++r) { const f32x4 s4 = *(const LAS f32x4*)(S + r * 1024 + k + 4 * q);
;                         acc[r] += wv[4 * q] * s4[0]; acc[r] += wv[4 * q + 1] * s4[1]; acc[r] += wv[4 * q + 2] * s4[2]; acc[r] += wv[4 * q + 3] * s4[3]; } }
	v_pk_fma_f32 v[36:37], v[78:79], v[40:41], v[184:185] op_sel_hi:[1,0,1]
	v_mov_b32_e32 v56, v21
	s_waitcnt lgkmcnt(1)
	v_pk_fma_f32 v[38:39], v[78:79], v[0:1], v[186:187] op_sel_hi:[1,0,1]
	v_pk_fma_f32 v[36:37], v[80:81], v[40:41], v[36:37] op_sel:[0,1,0]
	v_pk_fma_f32 v[0:1], v[80:81], v[0:1], v[38:39] op_sel:[0,1,0]
	v_pk_fma_f32 v[36:37], v[82:83], v[42:43], v[36:37] op_sel_hi:[1,0,1]
	v_mov_b32_e32 v40, v43
	v_pk_fma_f32 v[42:43], v[82:83], v[2:3], v[0:1] op_sel_hi:[1,0,1]
	s_waitcnt lgkmcnt(0)
	v_pk_fma_f32 v[0:1], v[78:79], v[46:47], v[188:189] op_sel_hi:[1,0,1]
	v_mov_b32_e32 v44, v3
	v_pk_fma_f32 v[0:1], v[80:81], v[46:47], v[0:1] op_sel:[0,1,0]
	v_mov_b32_e32 v38, v49
	v_pk_fma_f32 v[46:47], v[82:83], v[48:49], v[0:1] op_sel_hi:[1,0,1]
	ds_read_b128 v[48:51], v103
	ds_read_b128 v[0:3], v133
	s_waitcnt vmcnt(8)
	v_mov_b32_e32 v14, v234
	v_mov_b32_e32 v15, v235
	v_pk_fma_f32 v[58:59], v[14:15], v[56:57], v[58:59] op_sel_hi:[1,0,1]
	v_pk_fma_f32 v[54:55], v[14:15], v[54:55], v[52:53] op_sel_hi:[1,0,1]
	v_pk_fma_f32 v[168:169], v[14:15], v[66:67], v[62:63] op_sel_hi:[1,0,1]
	s_waitcnt lgkmcnt(1)
	v_pk_fma_f32 v[132:133], v[78:79], v[48:49], v[190:191] op_sel_hi:[1,0,1]
	s_waitcnt lgkmcnt(0)
	v_pk_fma_f32 v[130:131], v[78:79], v[0:1], v[130:131] op_sel_hi:[1,0,1]
	v_pk_fma_f32 v[48:49], v[80:81], v[48:49], v[132:133] op_sel:[0,1,0]
	v_pk_fma_f32 v[0:1], v[80:81], v[0:1], v[130:131] op_sel:[0,1,0]
	v_pk_fma_f32 v[62:63], v[14:15], v[100:101], v[104:105] op_sel_hi:[1,0,1]
	v_pk_fma_f32 v[130:131], v[82:83], v[2:3], v[0:1] op_sel_hi:[1,0,1]
	v_mov_b32_e32 v0, s6
	v_mov_b32_e32 v1, s7
	ds_read_b128 v[132:135], v0
	ds_read_b128 v[136:139], v1
	s_add_i32 s6, s3, 0xffff6fe0
	s_add_i32 s7, s3, 0xffff7fe0
	v_mov_b32_e32 v2, v3
	s_waitcnt lgkmcnt(1)
	v_pk_fma_f32 v[0:1], v[78:79], v[132:133], v[128:129] op_sel_hi:[1,0,1]
	v_mov_b32_e32 v27, s8
	v_pk_fma_f32 v[0:1], v[80:81], v[132:133], v[0:1] op_sel:[0,1,0]
	v_mov_b32_e32 v29, s9
	v_pk_fma_f32 v[128:129], v[82:83], v[134:135], v[0:1] op_sel_hi:[1,0,1]
	s_waitcnt lgkmcnt(0)
	v_pk_fma_f32 v[0:1], v[78:79], v[136:137], v[126:127] op_sel_hi:[1,0,1]
	v_mov_b32_e32 v134, v139
	v_pk_fma_f32 v[0:1], v[80:81], v[136:137], v[0:1] op_sel:[0,1,0]
	v_pk_fma_f32 v[176:177], v[14:15], v[26:27], v[34:35] op_sel_hi:[1,0,1]
	v_pk_fma_f32 v[126:127], v[82:83], v[138:139], v[0:1] op_sel_hi:[1,0,1]
	v_mov_b32_e32 v0, s6
	v_mov_b32_e32 v1, s7
	ds_read_b128 v[136:139], v0
	ds_read_b128 v[140:143], v1
	s_add_i32 s6, s3, 0xffff8fe0
	s_add_i32 s7, s3, 0xffff9fe0
	v_mov_b32_e32 v33, s14
	s_waitcnt lgkmcnt(1)
	v_pk_fma_f32 v[0:1], v[78:79], v[136:137], v[124:125] op_sel_hi:[1,0,1]
	v_pk_fma_f32 v[174:175], v[14:15], v[32:33], v[30:31] op_sel_hi:[1,0,1]
	v_pk_fma_f32 v[0:1], v[80:81], v[136:137], v[0:1] op_sel:[0,1,0]
	s_add_i32 s16, s3, 0xfffe4ff0
	v_pk_fma_f32 v[124:125], v[82:83], v[138:139], v[0:1] op_sel_hi:[1,0,1]
	s_waitcnt lgkmcnt(0)
	v_pk_fma_f32 v[0:1], v[78:79], v[140:141], v[122:123] op_sel_hi:[1,0,1]
	v_mov_b32_e32 v138, v143
	v_pk_fma_f32 v[0:1], v[80:81], v[140:141], v[0:1] op_sel:[0,1,0]
	v_pk_fma_f32 v[48:49], v[82:83], v[50:51], v[48:49] op_sel_hi:[1,0,1]
	v_pk_fma_f32 v[122:123], v[82:83], v[142:143], v[0:1] op_sel_hi:[1,0,1]
	v_mov_b32_e32 v0, s6
	v_mov_b32_e32 v1, s7
	ds_read_b128 v[140:143], v0
	ds_read_b128 v[144:147], v1
	s_add_i32 s6, s3, 0xffffafe0
	s_add_i32 s7, s3, 0xffffbfe0
	s_add_i32 s21, s3, 0xfffe9ff0
	s_waitcnt lgkmcnt(1)
	v_pk_fma_f32 v[0:1], v[78:79], v[140:141], v[120:121] op_sel_hi:[1,0,1]
	v_mov_b32_e32 v39, s15
	v_pk_fma_f32 v[0:1], v[80:81], v[140:141], v[0:1] op_sel:[0,1,0]
	v_mov_b32_e32 v41, s16
	v_pk_fma_f32 v[120:121], v[82:83], v[142:143], v[0:1] op_sel_hi:[1,0,1]
	s_waitcnt lgkmcnt(0)
	v_pk_fma_f32 v[0:1], v[78:79], v[144:145], v[118:119] op_sel_hi:[1,0,1]
	v_mov_b32_e32 v142, v147
	v_pk_fma_f32 v[0:1], v[80:81], v[144:145], v[0:1] op_sel:[0,1,0]
	v_mov_b32_e32 v132, v135
	v_pk_fma_f32 v[118:119], v[82:83], v[146:147], v[0:1] op_sel_hi:[1,0,1]
	v_mov_b32_e32 v0, s6
	v_mov_b32_e32 v1, s7
	ds_read_b128 v[144:147], v0
	ds_read_b128 v[148:151], v1
	s_add_i32 s6, s3, 0xffffcfe0
	s_add_i32 s7, s3, 0xffffdfe0
	v_pk_fma_f32 v[180:181], v[14:15], v[40:41], v[36:37] op_sel_hi:[1,0,1]
	s_waitcnt lgkmcnt(1)
	v_pk_fma_f32 v[0:1], v[78:79], v[144:145], v[116:117] op_sel_hi:[1,0,1]
	v_mov_b32_e32 v133, s21
	v_pk_fma_f32 v[0:1], v[80:81], v[144:145], v[0:1] op_sel:[0,1,0]
	v_pk_fma_f32 v[184:185], v[14:15], v[38:39], v[46:47] op_sel_hi:[1,0,1]
	v_pk_fma_f32 v[116:117], v[82:83], v[146:147], v[0:1] op_sel_hi:[1,0,1]
	s_waitcnt lgkmcnt(0)
	v_pk_fma_f32 v[0:1], v[78:79], v[148:149], v[114:115] op_sel_hi:[1,0,1]
	v_mov_b32_e32 v146, v151
	v_pk_fma_f32 v[0:1], v[80:81], v[148:149], v[0:1] op_sel:[0,1,0]
	s_add_i32 s17, s3, 0xfffe5ff0
	v_pk_fma_f32 v[114:115], v[82:83], v[150:151], v[0:1] op_sel_hi:[1,0,1]
	v_mov_b32_e32 v0, s6
	v_mov_b32_e32 v1, s7
	ds_read_b128 v[148:151], v0
	ds_read_b128 v[152:155], v1
	s_add_i32 s6, s3, 0xffffefe0
	s_sub_i32 s7, s3, 32
	v_mov_b32_e32 v136, v139
	s_waitcnt lgkmcnt(1)
	v_pk_fma_f32 v[0:1], v[78:79], v[148:149], v[112:113] op_sel_hi:[1,0,1]
	v_mov_b32_e32 v45, s17
	v_pk_fma_f32 v[0:1], v[80:81], v[148:149], v[0:1] op_sel:[0,1,0]
	v_mov_b32_e32 v148, v151
	v_pk_fma_f32 v[112:113], v[82:83], v[150:151], v[0:1] op_sel_hi:[1,0,1]
	s_waitcnt lgkmcnt(0)
	v_pk_fma_f32 v[0:1], v[78:79], v[152:153], v[110:111] op_sel_hi:[1,0,1]
	v_mov_b32_e32 v150, v155
	v_pk_fma_f32 v[0:1], v[80:81], v[152:153], v[0:1] op_sel:[0,1,0]
	v_pk_fma_f32 v[182:183], v[14:15], v[44:45], v[42:43] op_sel_hi:[1,0,1]
	v_pk_fma_f32 v[110:111], v[82:83], v[154:155], v[0:1] op_sel_hi:[1,0,1]
	v_mov_b32_e32 v0, s6
	v_mov_b32_e32 v1, s7
	ds_read_b128 v[152:155], v0
	ds_read_b128 v[170:173], v1
	s_mov_b32 s6, 0xfffac000
	s_add_i32 s7, s3, 0xfffdfff0
	s_add_i32 s18, s3, 0xfffe6ff0
	s_waitcnt lgkmcnt(1)
; #define LAS __attribute__((address_space(3)))
; __device__ __forceinline__ void phase0(CArgs a, LAS unsigned char* lds, int tid, int lane, int wave, int G, int bx) {
;     ...
;                 for (int i = 0; i < 16; ++i) wv[i] = __builtin_nontemporal_load((const f32x2*)(wp + (size_t)i * NMOD));
; #pragma unroll
;                 for (int q = 0; q < 4; ++q) {
; #pragma unroll
;                     for (int r = 0; r < NB; ++r) { const f32x4 s4 = *(const LAS f32x4*)(S + r * 1024 + k + 4 * q);
;                         acc[r] += wv[4 * q] * s4[0]; acc[r] += wv[4 * q + 1] * s4[1]; acc[r] += wv[4 * q + 2] * s4[2]; acc[r] += wv[4 * q + 3] * s4[3]; } }
	v_pk_fma_f32 v[0:1], v[78:79], v[152:153], v[68:69] op_sel_hi:[1,0,1]
	v_mov_b32_e32 v158, v155
	v_pk_fma_f32 v[0:1], v[80:81], v[152:153], v[0:1] op_sel:[0,1,0]
	v_pk_fma_f32 v[152:153], v[14:15], v[74:75], v[72:73] op_sel_hi:[1,0,1]
	v_pk_fma_f32 v[156:157], v[82:83], v[154:155], v[0:1] op_sel_hi:[1,0,1]
	s_waitcnt lgkmcnt(0)
	v_pk_fma_f32 v[0:1], v[78:79], v[170:171], v[60:61] op_sel_hi:[1,0,1]
	v_pk_fma_f32 v[154:155], v[14:15], v[64:65], v[70:71] op_sel_hi:[1,0,1]
	v_pk_fma_f32 v[0:1], v[80:81], v[170:171], v[0:1] op_sel:[0,1,0]
	v_pk_fma_f32 v[78:79], v[14:15], v[88:89], v[92:93] op_sel_hi:[1,0,1]
	v_pk_fma_f32 v[170:171], v[82:83], v[172:173], v[0:1] op_sel_hi:[1,0,1]
	v_add_co_u32_e32 v0, vcc, s6, v12
	s_mov_b32 s6, 0xfffb8000
	s_nop 0
	v_addc_co_u32_e32 v1, vcc, -1, v13, vcc
	v_add_co_u32_e32 v64, vcc, s6, v12
	s_mov_b32 s6, 0xfffc4000
	s_nop 0
	v_addc_co_u32_e32 v65, vcc, -1, v13, vcc
	v_add_co_u32_e32 v56, vcc, s6, v12
	s_mov_b32 s6, 0xfffd0000
	s_nop 0
	v_addc_co_u32_e32 v57, vcc, -1, v13, vcc
	v_add_co_u32_e32 v52, vcc, s6, v12
	s_add_i32 s6, s3, 0xfffdeff0
	s_nop 0
	v_addc_co_u32_e32 v53, vcc, -1, v13, vcc
	s_nop 0
	v_mov_b32_e32 v3, s6
	v_pk_fma_f32 v[74:75], v[14:15], v[96:97], v[94:95] op_sel_hi:[1,0,1]
	v_pk_fma_f32 v[70:71], v[14:15], v[102:103], v[98:99] op_sel_hi:[1,0,1]
	v_pk_fma_f32 v[94:95], v[14:15], v[20:21], v[18:19] op_sel_hi:[1,0,1]
	v_pk_fma_f32 v[98:99], v[14:15], v[16:17], v[22:23] op_sel_hi:[1,0,1]
	ds_read_b128 v[16:19], v3
	v_mov_b32_e32 v20, s7
	ds_read_b128 v[20:23], v20
	v_mov_b32_e32 v160, v173
	v_pk_fma_f32 v[172:173], v[14:15], v[28:29], v[24:25] op_sel_hi:[1,0,1]
	ds_read_b128 v[24:27], v27
	ds_read_b128 v[28:31], v29
	v_pk_fma_f32 v[52:53], v[14:15], v[2:3], v[130:131] op_sel_hi:[1,0,1]
	ds_read_b128 v[32:35], v33
	ds_read_b128 v[36:39], v39
	v_pk_fma_f32 v[82:83], v[14:15], v[90:91], v[86:87] op_sel_hi:[1,0,1]
	v_pk_fma_f32 v[90:91], v[14:15], v[148:149], v[112:113] op_sel_hi:[1,0,1]
	v_pk_fma_f32 v[56:57], v[14:15], v[132:133], v[128:129] op_sel_hi:[1,0,1]
	v_pk_fma_f32 v[64:65], v[14:15], v[136:137], v[124:125] op_sel_hi:[1,0,1]
	ds_read_b128 v[40:43], v41
	ds_read_b128 v[44:47], v45
	s_add_i32 s22, s3, 0xfffeaff0
	s_add_i32 s23, s3, 0xfffebff0
	s_add_i32 s24, s3, 0xfffecff0
	s_add_i32 s25, s3, 0xfffedff0
	s_add_i32 s29, s3, 0xffff1ff0
	s_add_i32 s30, s3, 0xffff2ff0
	v_mov_b32_e32 v50, v51
	v_mov_b32_e32 v140, v143
	v_mov_b32_e32 v144, v147
	v_pk_fma_f32 v[86:87], v[14:15], v[84:85], v[76:77] op_sel_hi:[1,0,1]
	v_mov_b32_e32 v51, s18
	v_mov_b32_e32 v135, s22
	v_mov_b32_e32 v139, s23
	v_mov_b32_e32 v141, s24
	v_mov_b32_e32 v147, s25
	v_mov_b32_e32 v151, s29
	v_mov_b32_e32 v159, s30
	v_pk_fma_f32 v[76:77], v[14:15], v[142:143], v[118:119] op_sel_hi:[1,0,1]
	v_pk_fma_f32 v[60:61], v[14:15], v[108:109], v[106:107] op_sel_hi:[1,0,1]
	s_add_i32 s19, s3, 0xfffe7ff0
	v_pk_fma_f32 v[186:187], v[14:15], v[50:51], v[48:49] op_sel_hi:[1,0,1]
	v_pk_fma_f32 v[66:67], v[14:15], v[134:135], v[126:127] op_sel_hi:[1,0,1]
	v_pk_fma_f32 v[68:69], v[14:15], v[138:139], v[122:123] op_sel_hi:[1,0,1]
	v_pk_fma_f32 v[72:73], v[14:15], v[140:141], v[120:121] op_sel_hi:[1,0,1]
	v_pk_fma_f32 v[80:81], v[14:15], v[144:145], v[116:117] op_sel_hi:[1,0,1]
	v_pk_fma_f32 v[84:85], v[14:15], v[146:147], v[114:115] op_sel_hi:[1,0,1]
	v_pk_fma_f32 v[96:97], v[14:15], v[150:151], v[110:111] op_sel_hi:[1,0,1]
	v_pk_fma_f32 v[110:111], v[14:15], v[158:159], v[156:157] op_sel_hi:[1,0,1]
	v_pk_fma_f32 v[102:103], v[14:15], v[160:161], v[170:171] op_sel_hi:[1,0,1]
	v_mov_b32_e32 v107, s19
	s_add_i32 s20, s3, 0xfffe8ff0
	s_waitcnt lgkmcnt(7)
	v_mov_b32_e32 v108, v19
	v_mov_b32_e32 v109, s20
	s_waitcnt lgkmcnt(6)
	v_mov_b32_e32 v106, v23
	s_waitcnt lgkmcnt(4)
	v_mov_b32_e32 v140, v31
	s_waitcnt lgkmcnt(3)
	v_mov_b32_e32 v138, v35
	v_mov_b32_e32 v132, v27
	s_add_i32 s26, s3, 0xfffeeff0
	s_waitcnt lgkmcnt(2)
	v_mov_b32_e32 v146, v39
	v_mov_b32_e32 v48, s26
	s_add_i32 s27, s3, 0xfffefff0
	s_add_i32 s28, s3, 0xffff0ff0
	v_mov_b32_e32 v49, s27
	v_mov_b32_e32 v50, s28
	s_waitcnt lgkmcnt(0)
	v_mov_b32_e32 v150, v47
	s_add_i32 s31, s3, 0xffff3ff0
	v_mov_b32_e32 v188, s31
	s_add_i32 s6, s3, 0xffff4ff0
	s_add_i32 s7, s3, 0xffff5ff0
	s_add_i32 s8, s3, 0xfffe1000
	s_add_i32 s9, s3, 0xfffe2000
	s_add_i32 s14, s3, 0xfffe3000
	s_add_i32 s17, s3, 0xfffe6000
	s_add_i32 s15, s3, 0xfffe4000
	s_add_i32 s16, s3, 0xfffe5000
	s_add_i32 s18, s3, 0xfffe7000
	s_waitcnt vmcnt(7)
	v_mov_b32_e32 v88, v236
	v_mov_b32_e32 v89, v237
	v_pk_fma_f32 v[2:3], v[88:89], v[16:17], v[168:169] op_sel_hi:[1,0,1]
	s_add_i32 s19, s3, 0xfffe8000
	s_waitcnt vmcnt(6)
	v_mov_b32_e32 v92, v238
	v_mov_b32_e32 v93, v239
	v_pk_fma_f32 v[2:3], v[92:93], v[16:17], v[2:3] op_sel:[0,1,0]
	ds_read_b128 v[14:17], v51
	s_waitcnt vmcnt(5)
	v_mov_b32_e32 v100, v240
	v_mov_b32_e32 v101, v241
	v_pk_fma_f32 v[104:105], v[100:101], v[18:19], v[2:3] op_sel_hi:[1,0,1]
	v_pk_fma_f32 v[2:3], v[88:89], v[20:21], v[154:155] op_sel_hi:[1,0,1]
	s_add_i32 s20, s3, 0xfffe9000
	v_pk_fma_f32 v[2:3], v[92:93], v[20:21], v[2:3] op_sel:[0,1,0]
	ds_read_b128 v[18:21], v107
	v_pk_fma_f32 v[112:113], v[100:101], v[22:23], v[2:3] op_sel_hi:[1,0,1]
	v_pk_fma_f32 v[2:3], v[88:89], v[24:25], v[152:153] op_sel_hi:[1,0,1]
	v_mov_b32_e32 v152, v43
	v_pk_fma_f32 v[2:3], v[92:93], v[24:25], v[2:3] op_sel:[0,1,0]
	ds_read_b128 v[22:25], v109
	v_pk_fma_f32 v[128:129], v[100:101], v[26:27], v[2:3] op_sel_hi:[1,0,1]
	v_pk_fma_f32 v[2:3], v[88:89], v[28:29], v[82:83] op_sel_hi:[1,0,1]
	s_waitcnt lgkmcnt(2)
; #define LAS __attribute__((address_space(3)))
; __device__ __forceinline__ void phase0(CArgs a, LAS unsigned char* lds, int tid, int lane, int wave, int G, int bx) {
;     ...
;                 for (int i = 0; i < 16; ++i) wv[i] = __builtin_nontemporal_load((const f32x2*)(wp + (size_t)i * NMOD));
; #pragma unroll
;                 for (int q = 0; q < 4; ++q) {
; #pragma unroll
;                     for (int r = 0; r < NB; ++r) { const f32x4 s4 = *(const LAS f32x4*)(S + r * 1024 + k + 4 * q);
;                         acc[r] += wv[4 * q] * s4[0]; acc[r] += wv[4 * q + 1] * s4[1]; acc[r] += wv[4 * q + 2] * s4[2]; acc[r] += wv[4 * q + 3] * s4[3]; } }
	v_mov_b32_e32 v158, v17
	v_pk_fma_f32 v[2:3], v[92:93], v[28:29], v[2:3] op_sel:[0,1,0]
	ds_read_b128 v[26:29], v133
	v_pk_fma_f32 v[136:137], v[100:101], v[30:31], v[2:3] op_sel_hi:[1,0,1]
	v_pk_fma_f32 v[2:3], v[88:89], v[32:33], v[78:79] op_sel_hi:[1,0,1]
	s_waitcnt lgkmcnt(1)
	v_mov_b32_e32 v124, v25
	v_pk_fma_f32 v[2:3], v[92:93], v[32:33], v[2:3] op_sel:[0,1,0]
	ds_read_b128 v[30:33], v135
	v_pk_fma_f32 v[142:143], v[100:101], v[34:35], v[2:3] op_sel_hi:[1,0,1]
	v_pk_fma_f32 v[2:3], v[88:89], v[36:37], v[74:75] op_sel_hi:[1,0,1]
	v_mov_b32_e32 v134, v21
	v_pk_fma_f32 v[2:3], v[92:93], v[36:37], v[2:3] op_sel:[0,1,0]
	ds_read_b128 v[34:37], v139
	v_pk_fma_f32 v[144:145], v[100:101], v[38:39], v[2:3] op_sel_hi:[1,0,1]
	v_pk_fma_f32 v[2:3], v[88:89], v[40:41], v[70:71] op_sel_hi:[1,0,1]
	s_waitcnt vmcnt(4)
	v_mov_b32_e32 v0, v242
	v_mov_b32_e32 v1, v243
	v_pk_fma_f32 v[112:113], v[0:1], v[106:107], v[112:113] op_sel_hi:[1,0,1]
	v_pk_fma_f32 v[2:3], v[92:93], v[40:41], v[2:3] op_sel:[0,1,0]
	ds_read_b128 v[38:41], v141
	v_pk_fma_f32 v[148:149], v[100:101], v[42:43], v[2:3] op_sel_hi:[1,0,1]
	v_pk_fma_f32 v[2:3], v[88:89], v[44:45], v[62:63] op_sel_hi:[1,0,1]
	s_add_i32 s21, s3, 0xfffea000
	v_pk_fma_f32 v[2:3], v[92:93], v[44:45], v[2:3] op_sel:[0,1,0]
	ds_read_b128 v[42:45], v147
	v_pk_fma_f32 v[154:155], v[100:101], v[46:47], v[2:3] op_sel_hi:[1,0,1]
	v_pk_fma_f32 v[2:3], v[88:89], v[14:15], v[60:61] op_sel_hi:[1,0,1]
	s_add_i32 s22, s3, 0xfffeb000
	v_pk_fma_f32 v[2:3], v[92:93], v[14:15], v[2:3] op_sel:[0,1,0]
	s_waitcnt lgkmcnt(3)
	v_pk_fma_f32 v[14:15], v[88:89], v[30:31], v[94:95] op_sel_hi:[1,0,1]
	v_pk_fma_f32 v[156:157], v[100:101], v[16:17], v[2:3] op_sel_hi:[1,0,1]
	v_pk_fma_f32 v[2:3], v[88:89], v[18:19], v[86:87] op_sel_hi:[1,0,1]
	v_pk_fma_f32 v[14:15], v[92:93], v[30:31], v[14:15] op_sel:[0,1,0]
	v_pk_fma_f32 v[2:3], v[92:93], v[18:19], v[2:3] op_sel:[0,1,0]
	v_pk_fma_f32 v[18:19], v[100:101], v[32:33], v[14:15] op_sel_hi:[1,0,1]
	v_pk_fma_f32 v[130:131], v[100:101], v[20:21], v[2:3] op_sel_hi:[1,0,1]
	v_pk_fma_f32 v[2:3], v[88:89], v[22:23], v[58:59] op_sel_hi:[1,0,1]
	s_waitcnt lgkmcnt(2)
	v_mov_b32_e32 v14, v37
	v_pk_fma_f32 v[2:3], v[92:93], v[22:23], v[2:3] op_sel:[0,1,0]
	v_pk_fma_f32 v[22:23], v[88:89], v[34:35], v[98:99] op_sel_hi:[1,0,1]
	v_pk_fma_f32 v[126:127], v[100:101], v[24:25], v[2:3] op_sel_hi:[1,0,1]
	v_pk_fma_f32 v[22:23], v[92:93], v[34:35], v[22:23] op_sel:[0,1,0]
	v_pk_fma_f32 v[2:3], v[88:89], v[26:27], v[54:55] op_sel_hi:[1,0,1]
	v_pk_fma_f32 v[22:23], v[100:101], v[36:37], v[22:23] op_sel_hi:[1,0,1]
	ds_read_b128 v[34:37], v48
	s_waitcnt lgkmcnt(2)
	v_pk_fma_f32 v[24:25], v[88:89], v[38:39], v[172:173] op_sel_hi:[1,0,1]
	v_pk_fma_f32 v[2:3], v[92:93], v[26:27], v[2:3] op_sel:[0,1,0]
	v_pk_fma_f32 v[24:25], v[92:93], v[38:39], v[24:25] op_sel:[0,1,0]
	s_waitcnt lgkmcnt(1)
	v_pk_fma_f32 v[26:27], v[88:89], v[42:43], v[174:175] op_sel_hi:[1,0,1]
	v_pk_fma_f32 v[2:3], v[100:101], v[28:29], v[2:3] op_sel_hi:[1,0,1]
	v_pk_fma_f32 v[24:25], v[100:101], v[40:41], v[24:25] op_sel_hi:[1,0,1]
	v_mov_b32_e32 v28, v41
	ds_read_b128 v[38:41], v49
	v_pk_fma_f32 v[26:27], v[92:93], v[42:43], v[26:27] op_sel:[0,1,0]
	s_waitcnt lgkmcnt(1)
	v_pk_fma_f32 v[42:43], v[88:89], v[34:35], v[176:177] op_sel_hi:[1,0,1]
	v_pk_fma_f32 v[30:31], v[100:101], v[44:45], v[26:27] op_sel_hi:[1,0,1]
	v_mov_b32_e32 v32, v45
	v_pk_fma_f32 v[34:35], v[92:93], v[34:35], v[42:43] op_sel:[0,1,0]
	ds_read_b128 v[42:45], v50
	ds_read_b128 v[46:49], v151
	v_mov_b32_e32 v26, v37
	v_pk_fma_f32 v[34:35], v[100:101], v[36:37], v[34:35] op_sel_hi:[1,0,1]
	s_waitcnt lgkmcnt(2)
	v_pk_fma_f32 v[36:37], v[88:89], v[38:39], v[180:181] op_sel_hi:[1,0,1]
	v_mov_b32_e32 v15, s6
	v_pk_fma_f32 v[36:37], v[92:93], v[38:39], v[36:37] op_sel:[0,1,0]
	s_waitcnt lgkmcnt(1)
	v_pk_fma_f32 v[38:39], v[88:89], v[42:43], v[182:183] op_sel_hi:[1,0,1]
	s_waitcnt lgkmcnt(0)
	v_pk_fma_f32 v[50:51], v[88:89], v[46:47], v[184:185] op_sel_hi:[1,0,1]
	v_pk_fma_f32 v[38:39], v[92:93], v[42:43], v[38:39] op_sel:[0,1,0]
	v_pk_fma_f32 v[46:47], v[92:93], v[46:47], v[50:51] op_sel:[0,1,0]
	v_pk_fma_f32 v[42:43], v[100:101], v[44:45], v[38:39] op_sel_hi:[1,0,1]
	v_mov_b32_e32 v38, v49
	v_pk_fma_f32 v[46:47], v[100:101], v[48:49], v[46:47] op_sel_hi:[1,0,1]
	ds_read_b128 v[48:51], v159
	ds_read_b128 v[58:61], v188
	v_mov_b32_e32 v17, s7
	s_add_i32 s6, s3, 0xffff6ff0
	s_add_i32 s7, s3, 0xffff7ff0
	s_waitcnt lgkmcnt(1)
	v_pk_fma_f32 v[54:55], v[88:89], v[48:49], v[186:187] op_sel_hi:[1,0,1]
	s_waitcnt lgkmcnt(0)
	v_pk_fma_f32 v[52:53], v[88:89], v[58:59], v[52:53] op_sel_hi:[1,0,1]
	v_pk_fma_f32 v[48:49], v[92:93], v[48:49], v[54:55] op_sel:[0,1,0]
	v_pk_fma_f32 v[52:53], v[92:93], v[58:59], v[52:53] op_sel:[0,1,0]
	v_mov_b32_e32 v54, v61
	v_pk_fma_f32 v[52:53], v[100:101], v[60:61], v[52:53] op_sel_hi:[1,0,1]
	ds_read_b128 v[58:61], v15
	ds_read_b128 v[114:117], v17
	v_mov_b32_e32 v15, s6
	v_mov_b32_e32 v17, s7
	s_add_i32 s6, s3, 0xffff8ff0
	s_waitcnt lgkmcnt(1)
	v_pk_fma_f32 v[56:57], v[88:89], v[58:59], v[56:57] op_sel_hi:[1,0,1]
	s_waitcnt lgkmcnt(0)
	v_mov_b32_e32 v62, v117
	v_pk_fma_f32 v[56:57], v[92:93], v[58:59], v[56:57] op_sel:[0,1,0]
	v_mov_b32_e32 v58, v61
	v_pk_fma_f32 v[56:57], v[100:101], v[60:61], v[56:57] op_sel_hi:[1,0,1]
	v_pk_fma_f32 v[60:61], v[88:89], v[114:115], v[66:67] op_sel_hi:[1,0,1]
	s_add_i32 s7, s3, 0xffff9ff0
	v_pk_fma_f32 v[60:61], v[92:93], v[114:115], v[60:61] op_sel:[0,1,0]
	v_pk_fma_f32 v[176:177], v[0:1], v[124:125], v[126:127] op_sel_hi:[1,0,1]
	v_pk_fma_f32 v[60:61], v[100:101], v[116:117], v[60:61] op_sel_hi:[1,0,1]
	ds_read_b128 v[114:117], v15
	ds_read_b128 v[118:121], v17
	v_mov_b32_e32 v15, s6
	v_mov_b32_e32 v17, s7
	s_add_i32 s6, s3, 0xffffaff0
	s_waitcnt lgkmcnt(1)
; #define LAS __attribute__((address_space(3)))
; __device__ __forceinline__ void phase0(CArgs a, LAS unsigned char* lds, int tid, int lane, int wave, int G, int bx) {
;     ...
;                 for (int i = 0; i < 16; ++i) wv[i] = __builtin_nontemporal_load((const f32x2*)(wp + (size_t)i * NMOD));
; #pragma unroll
;                 for (int q = 0; q < 4; ++q) {
; #pragma unroll
;                     for (int r = 0; r < NB; ++r) { const f32x4 s4 = *(const LAS f32x4*)(S + r * 1024 + k + 4 * q);
;                         acc[r] += wv[4 * q] * s4[0]; acc[r] += wv[4 * q + 1] * s4[1]; acc[r] += wv[4 * q + 2] * s4[2]; acc[r] += wv[4 * q + 3] * s4[3]; } }
	v_pk_fma_f32 v[64:65], v[88:89], v[114:115], v[64:65] op_sel_hi:[1,0,1]
	s_waitcnt lgkmcnt(0)
	v_pk_fma_f32 v[68:69], v[88:89], v[118:119], v[68:69] op_sel_hi:[1,0,1]
	v_pk_fma_f32 v[64:65], v[92:93], v[114:115], v[64:65] op_sel:[0,1,0]
	v_pk_fma_f32 v[68:69], v[92:93], v[118:119], v[68:69] op_sel:[0,1,0]
	v_pk_fma_f32 v[64:65], v[100:101], v[116:117], v[64:65] op_sel_hi:[1,0,1]
	v_mov_b32_e32 v66, v117
	v_pk_fma_f32 v[68:69], v[100:101], v[120:121], v[68:69] op_sel_hi:[1,0,1]
	v_mov_b32_e32 v70, v121
	ds_read_b128 v[114:117], v15
	ds_read_b128 v[118:121], v17
	s_add_i32 s7, s3, 0xffffbff0
	v_mov_b32_e32 v15, s6
	v_mov_b32_e32 v17, s7
	s_waitcnt lgkmcnt(1)
	v_pk_fma_f32 v[72:73], v[88:89], v[114:115], v[72:73] op_sel_hi:[1,0,1]
	s_waitcnt lgkmcnt(0)
	v_pk_fma_f32 v[76:77], v[88:89], v[118:119], v[76:77] op_sel_hi:[1,0,1]
	v_pk_fma_f32 v[72:73], v[92:93], v[114:115], v[72:73] op_sel:[0,1,0]
	v_pk_fma_f32 v[76:77], v[92:93], v[118:119], v[76:77] op_sel:[0,1,0]
	v_pk_fma_f32 v[72:73], v[100:101], v[116:117], v[72:73] op_sel_hi:[1,0,1]
	v_mov_b32_e32 v74, v117
	v_pk_fma_f32 v[76:77], v[100:101], v[120:121], v[76:77] op_sel_hi:[1,0,1]
	v_mov_b32_e32 v78, v121
	ds_read_b128 v[114:117], v15
	ds_read_b128 v[118:121], v17
	s_add_i32 s6, s3, 0xffffcff0
	s_add_i32 s7, s3, 0xffffdff0
	v_mov_b32_e32 v15, s6
	s_waitcnt lgkmcnt(1)
	v_pk_fma_f32 v[80:81], v[88:89], v[114:115], v[80:81] op_sel_hi:[1,0,1]
	s_waitcnt lgkmcnt(0)
	v_pk_fma_f32 v[84:85], v[88:89], v[118:119], v[84:85] op_sel_hi:[1,0,1]
	v_pk_fma_f32 v[80:81], v[92:93], v[114:115], v[80:81] op_sel:[0,1,0]
	v_pk_fma_f32 v[84:85], v[92:93], v[118:119], v[84:85] op_sel:[0,1,0]
	v_pk_fma_f32 v[80:81], v[100:101], v[116:117], v[80:81] op_sel_hi:[1,0,1]
	v_mov_b32_e32 v82, v117
	v_pk_fma_f32 v[84:85], v[100:101], v[120:121], v[84:85] op_sel_hi:[1,0,1]
	v_mov_b32_e32 v86, v121
	v_mov_b32_e32 v17, s7
	ds_read_b128 v[114:117], v15
	ds_read_b128 v[118:121], v17
	s_add_i32 s6, s3, 0xffffeff0
	s_add_i32 s7, s3, -16
	v_mov_b32_e32 v15, s6
	s_waitcnt lgkmcnt(1)
	v_pk_fma_f32 v[90:91], v[88:89], v[114:115], v[90:91] op_sel_hi:[1,0,1]
	s_waitcnt lgkmcnt(0)
	v_pk_fma_f32 v[96:97], v[88:89], v[118:119], v[96:97] op_sel_hi:[1,0,1]
	v_pk_fma_f32 v[90:91], v[92:93], v[114:115], v[90:91] op_sel:[0,1,0]
	v_pk_fma_f32 v[96:97], v[92:93], v[118:119], v[96:97] op_sel:[0,1,0]
	v_pk_fma_f32 v[90:91], v[100:101], v[116:117], v[90:91] op_sel_hi:[1,0,1]
	v_mov_b32_e32 v94, v117
	v_pk_fma_f32 v[96:97], v[100:101], v[120:121], v[96:97] op_sel_hi:[1,0,1]
	v_mov_b32_e32 v98, v121
	v_mov_b32_e32 v17, s7
	ds_read_b128 v[114:117], v15
	ds_read_b128 v[120:123], v17
	s_mov_b32 s6, 0xfffdc000
	v_mov_b32_e32 v16, v29
	s_add_i32 s7, s3, 0xfffe0000
	s_waitcnt lgkmcnt(1)
	v_pk_fma_f32 v[110:111], v[88:89], v[114:115], v[110:111] op_sel_hi:[1,0,1]
	v_mov_b32_e32 v118, v117
	v_pk_fma_f32 v[110:111], v[92:93], v[114:115], v[110:111] op_sel:[0,1,0]
	v_pk_fma_f32 v[180:181], v[0:1], v[16:17], v[2:3] op_sel_hi:[1,0,1]
	v_pk_fma_f32 v[114:115], v[100:101], v[116:117], v[110:111] op_sel_hi:[1,0,1]
	v_pk_fma_f32 v[110:111], v[0:1], v[132:133], v[128:129] op_sel_hi:[1,0,1]
	v_add_co_u32_e32 v128, vcc, s6, v12
	s_mov_b32 s6, 0xfffe8000
	s_nop 0
	v_addc_co_u32_e32 v129, vcc, -1, v13, vcc
	v_pk_fma_f32 v[116:117], v[0:1], v[108:109], v[104:105] op_sel_hi:[1,0,1]
	v_pk_fma_f32 v[108:109], v[0:1], v[134:135], v[130:131] op_sel_hi:[1,0,1]
	v_add_co_u32_e32 v130, vcc, s6, v12
	s_mov_b32 s6, 0xffff4000
	s_nop 0
	v_addc_co_u32_e32 v131, vcc, -1, v13, vcc
	v_add_co_u32_e32 v124, vcc, s6, v12
	s_add_i32 s6, s3, 0xfffdf000
	s_nop 0
	v_addc_co_u32_e32 v125, vcc, -1, v13, vcc
	s_nop 0
	s_nop 0
	v_mov_b32_e32 v2, s6
	v_mov_b32_e32 v20, v33
	v_mov_b32_e32 v3, s7
	v_pk_fma_f32 v[184:185], v[0:1], v[14:15], v[22:23] op_sel_hi:[1,0,1]
	ds_read_b128 v[14:17], v2
	v_pk_fma_f32 v[182:183], v[0:1], v[20:21], v[18:19] op_sel_hi:[1,0,1]
	v_mov_b32_e32 v27, s8
	v_mov_b32_e32 v29, s9
	ds_read_b128 v[18:21], v3
	v_pk_fma_f32 v[186:187], v[0:1], v[28:29], v[24:25] op_sel_hi:[1,0,1]
	ds_read_b128 v[22:25], v27
	v_mov_b32_e32 v33, s14
	v_mov_b32_e32 v44, v45
	s_waitcnt lgkmcnt(3)
	v_pk_fma_f32 v[88:89], v[88:89], v[120:121], v[102:103] op_sel_hi:[1,0,1]
	v_mov_b32_e32 v45, s17
	v_pk_fma_f32 v[188:189], v[0:1], v[32:33], v[30:31] op_sel_hi:[1,0,1]
	v_pk_fma_f32 v[190:191], v[0:1], v[26:27], v[34:35] op_sel_hi:[1,0,1]
	ds_read_b128 v[30:33], v33
	ds_read_b128 v[26:29], v29
	v_pk_fma_f32 v[36:37], v[100:101], v[40:41], v[36:37] op_sel_hi:[1,0,1]
	v_mov_b32_e32 v40, v41
	v_pk_fma_f32 v[88:89], v[92:93], v[120:121], v[88:89] op_sel:[0,1,0]
	s_add_i32 s23, s3, 0xfffec000
	s_add_i32 s25, s3, 0xfffee000
	s_add_i32 s27, s3, 0xffff0000
	s_add_i32 s28, s3, 0xffff1000
	s_add_i32 s29, s3, 0xffff2000
	s_add_i32 s30, s3, 0xffff3000
	v_mov_b32_e32 v39, s15
	v_mov_b32_e32 v41, s16
	v_pk_fma_f32 v[194:195], v[0:1], v[44:45], v[42:43] op_sel_hi:[1,0,1]
	v_pk_fma_f32 v[48:49], v[100:101], v[50:51], v[48:49] op_sel_hi:[1,0,1]
	v_mov_b32_e32 v50, v51
	v_pk_fma_f32 v[120:121], v[100:101], v[122:123], v[88:89] op_sel_hi:[1,0,1]
	v_mov_b32_e32 v122, v123
	v_mov_b32_e32 v51, s18
	v_mov_b32_e32 v55, s19
	v_mov_b32_e32 v59, s20
	v_mov_b32_e32 v63, s21
	v_pk_fma_f32 v[192:193], v[0:1], v[40:41], v[36:37] op_sel_hi:[1,0,1]
	v_mov_b32_e32 v67, s22
	v_mov_b32_e32 v71, s23
	v_mov_b32_e32 v75, s25
	v_mov_b32_e32 v95, s27
	v_mov_b32_e32 v99, s28
	v_mov_b32_e32 v119, s29
	v_mov_b32_e32 v123, s30
	ds_read_b128 v[34:37], v39
	v_pk_fma_f32 v[106:107], v[0:1], v[140:141], v[136:137] op_sel_hi:[1,0,1]
	v_pk_fma_f32 v[104:105], v[0:1], v[138:139], v[142:143] op_sel_hi:[1,0,1]
	v_pk_fma_f32 v[102:103], v[0:1], v[146:147], v[144:145] op_sel_hi:[1,0,1]
	v_pk_fma_f32 v[100:101], v[0:1], v[152:153], v[148:149] op_sel_hi:[1,0,1]
	v_pk_fma_f32 v[92:93], v[0:1], v[150:151], v[154:155] op_sel_hi:[1,0,1]
	v_pk_fma_f32 v[88:89], v[0:1], v[158:159], v[156:157] op_sel_hi:[1,0,1]
	v_pk_fma_f32 v[196:197], v[0:1], v[38:39], v[46:47] op_sel_hi:[1,0,1]
	v_pk_fma_f32 v[198:199], v[0:1], v[50:51], v[48:49] op_sel_hi:[1,0,1]
	v_pk_fma_f32 v[200:201], v[0:1], v[54:55], v[52:53] op_sel_hi:[1,0,1]
	v_pk_fma_f32 v[202:203], v[0:1], v[58:59], v[56:57] op_sel_hi:[1,0,1]
	v_pk_fma_f32 v[204:205], v[0:1], v[62:63], v[60:61] op_sel_hi:[1,0,1]
	v_pk_fma_f32 v[174:175], v[0:1], v[66:67], v[64:65] op_sel_hi:[1,0,1]
	v_pk_fma_f32 v[172:173], v[0:1], v[70:71], v[68:69] op_sel_hi:[1,0,1]
	v_pk_fma_f32 v[170:171], v[0:1], v[74:75], v[72:73] op_sel_hi:[1,0,1]
	v_pk_fma_f32 v[168:169], v[0:1], v[78:79], v[76:77] op_sel_hi:[1,0,1]
	v_pk_fma_f32 v[158:159], v[0:1], v[82:83], v[80:81] op_sel_hi:[1,0,1]
	v_pk_fma_f32 v[156:157], v[0:1], v[86:87], v[84:85] op_sel_hi:[1,0,1]
	v_pk_fma_f32 v[154:155], v[0:1], v[94:95], v[90:91] op_sel_hi:[1,0,1]
	v_pk_fma_f32 v[152:153], v[0:1], v[98:99], v[96:97] op_sel_hi:[1,0,1]
	v_pk_fma_f32 v[124:125], v[0:1], v[118:119], v[114:115] op_sel_hi:[1,0,1]
	ds_read_b128 v[38:41], v41
	v_pk_fma_f32 v[86:87], v[0:1], v[122:123], v[120:121] op_sel_hi:[1,0,1]
	ds_read_b128 v[0:3], v45
	s_waitcnt lgkmcnt(7)
; #define LAS __attribute__((address_space(3)))
; __device__ __forceinline__ void phase0(CArgs a, LAS unsigned char* lds, int tid, int lane, int wave, int G, int bx) {
;     ...
;                 for (int i = 0; i < 16; ++i) wv[i] = __builtin_nontemporal_load((const f32x2*)(wp + (size_t)i * NMOD));
; #pragma unroll
;                 for (int q = 0; q < 4; ++q) {
; #pragma unroll
;                     for (int r = 0; r < NB; ++r) { const f32x4 s4 = *(const LAS f32x4*)(S + r * 1024 + k + 4 * q);
;                         acc[r] += wv[4 * q] * s4[0]; acc[r] += wv[4 * q + 1] * s4[1]; acc[r] += wv[4 * q + 2] * s4[2]; acc[r] += wv[4 * q + 3] * s4[3]; } }
	v_mov_b32_e32 v74, v17
	s_waitcnt lgkmcnt(6)
	v_mov_b32_e32 v80, v21
	s_waitcnt lgkmcnt(5)
	v_mov_b32_e32 v84, v25
	s_waitcnt lgkmcnt(3)
	v_mov_b32_e32 v132, v29
	s_add_i32 s24, s3, 0xfffed000
	v_mov_b32_e32 v138, v33
	s_waitcnt vmcnt(3)
	v_mov_b32_e32 v126, v244
	v_mov_b32_e32 v127, v245
	v_pk_fma_f32 v[42:43], v[126:127], v[14:15], v[116:117] op_sel_hi:[1,0,1]
	v_mov_b32_e32 v44, s24
	s_waitcnt vmcnt(2)
	v_mov_b32_e32 v128, v246
	v_mov_b32_e32 v129, v247
	v_pk_fma_f32 v[14:15], v[128:129], v[14:15], v[42:43] op_sel:[0,1,0]
	v_pk_fma_f32 v[42:43], v[126:127], v[18:19], v[112:113] op_sel_hi:[1,0,1]
	s_waitcnt vmcnt(1)
	v_mov_b32_e32 v130, v248
	v_mov_b32_e32 v131, v249
	v_pk_fma_f32 v[76:77], v[130:131], v[16:17], v[14:15] op_sel_hi:[1,0,1]
	v_pk_fma_f32 v[18:19], v[128:129], v[18:19], v[42:43] op_sel:[0,1,0]
	v_pk_fma_f32 v[42:43], v[126:127], v[22:23], v[110:111] op_sel_hi:[1,0,1]
	ds_read_b128 v[14:17], v51
	v_pk_fma_f32 v[22:23], v[128:129], v[22:23], v[42:43] op_sel:[0,1,0]
	v_pk_fma_f32 v[78:79], v[130:131], v[20:21], v[18:19] op_sel_hi:[1,0,1]
	v_pk_fma_f32 v[82:83], v[130:131], v[24:25], v[22:23] op_sel_hi:[1,0,1]
	v_pk_fma_f32 v[22:23], v[126:127], v[26:27], v[106:107] op_sel_hi:[1,0,1]
	ds_read_b128 v[18:21], v55
	v_pk_fma_f32 v[22:23], v[128:129], v[26:27], v[22:23] op_sel:[0,1,0]
	v_pk_fma_f32 v[26:27], v[126:127], v[30:31], v[104:105] op_sel_hi:[1,0,1]
	v_pk_fma_f32 v[134:135], v[130:131], v[28:29], v[22:23] op_sel_hi:[1,0,1]
	v_pk_fma_f32 v[26:27], v[128:129], v[30:31], v[26:27] op_sel:[0,1,0]
	s_waitcnt lgkmcnt(4)
	v_pk_fma_f32 v[30:31], v[126:127], v[34:35], v[102:103] op_sel_hi:[1,0,1]
	ds_read_b128 v[22:25], v59
	v_pk_fma_f32 v[30:31], v[128:129], v[34:35], v[30:31] op_sel:[0,1,0]
	s_waitcnt lgkmcnt(3)
	v_pk_fma_f32 v[34:35], v[126:127], v[0:1], v[92:93] op_sel_hi:[1,0,1]
	v_pk_fma_f32 v[136:137], v[130:131], v[32:33], v[26:27] op_sel_hi:[1,0,1]
	ds_read_b128 v[26:29], v63
	v_pk_fma_f32 v[140:141], v[130:131], v[36:37], v[30:31] op_sel_hi:[1,0,1]
	v_pk_fma_f32 v[30:31], v[126:127], v[38:39], v[100:101] op_sel_hi:[1,0,1]
	v_pk_fma_f32 v[0:1], v[128:129], v[0:1], v[34:35] op_sel:[0,1,0]
	v_pk_fma_f32 v[30:31], v[128:129], v[38:39], v[30:31] op_sel:[0,1,0]
	v_pk_fma_f32 v[148:149], v[130:131], v[2:3], v[0:1] op_sel_hi:[1,0,1]
	s_waitcnt lgkmcnt(3)
	v_pk_fma_f32 v[0:1], v[126:127], v[14:15], v[88:89] op_sel_hi:[1,0,1]
	v_pk_fma_f32 v[146:147], v[130:131], v[40:41], v[30:31] op_sel_hi:[1,0,1]
	ds_read_b128 v[30:33], v67
	v_pk_fma_f32 v[0:1], v[128:129], v[14:15], v[0:1] op_sel:[0,1,0]
	v_mov_b32_e32 v144, v37
	ds_read_b128 v[34:37], v71
	v_pk_fma_f32 v[0:1], v[130:131], v[16:17], v[0:1] op_sel_hi:[1,0,1]
	v_mov_b32_e32 v14, v17
	s_waitcnt lgkmcnt(4)
	v_pk_fma_f32 v[16:17], v[126:127], v[18:19], v[108:109] op_sel_hi:[1,0,1]
	s_add_i32 s26, s3, 0xfffef000
	v_mov_b32_e32 v142, v41
	v_pk_fma_f32 v[16:17], v[128:129], v[18:19], v[16:17] op_sel:[0,1,0]
	ds_read_b128 v[38:41], v44
	s_waitcnt lgkmcnt(4)
	v_pk_fma_f32 v[18:19], v[126:127], v[22:23], v[176:177] op_sel_hi:[1,0,1]
	v_mov_b32_e32 v46, s26
	v_pk_fma_f32 v[18:19], v[128:129], v[22:23], v[18:19] op_sel:[0,1,0]
	s_waitcnt lgkmcnt(3)
	v_pk_fma_f32 v[22:23], v[126:127], v[26:27], v[180:181] op_sel_hi:[1,0,1]
	ds_read_b128 v[46:49], v46
	ds_read_b128 v[42:45], v75
	ds_read_b128 v[50:53], v95
	v_pk_fma_f32 v[22:23], v[128:129], v[26:27], v[22:23] op_sel:[0,1,0]
	v_mov_b32_e32 v26, v29
	v_pk_fma_f32 v[22:23], v[130:131], v[28:29], v[22:23] op_sel_hi:[1,0,1]
	s_waitcnt lgkmcnt(5)
	v_pk_fma_f32 v[28:29], v[126:127], v[30:31], v[182:183] op_sel_hi:[1,0,1]
	ds_read_b128 v[54:57], v99
	ds_read_b128 v[58:61], v119
	v_pk_fma_f32 v[28:29], v[128:129], v[30:31], v[28:29] op_sel:[0,1,0]
	s_waitcnt lgkmcnt(6)
	v_pk_fma_f32 v[30:31], v[126:127], v[34:35], v[184:185] op_sel_hi:[1,0,1]
	s_add_i32 s31, s3, 0xffff4000
	v_pk_fma_f32 v[30:31], v[128:129], v[34:35], v[30:31] op_sel:[0,1,0]
	s_waitcnt lgkmcnt(5)
	v_pk_fma_f32 v[34:35], v[126:127], v[38:39], v[186:187] op_sel_hi:[1,0,1]
	v_mov_b32_e32 v133, s31
	v_pk_fma_f32 v[34:35], v[128:129], v[38:39], v[34:35] op_sel:[0,1,0]
	v_mov_b32_e32 v38, v41
	v_pk_fma_f32 v[34:35], v[130:131], v[40:41], v[34:35] op_sel_hi:[1,0,1]
	s_waitcnt lgkmcnt(3)
	v_pk_fma_f32 v[40:41], v[126:127], v[42:43], v[188:189] op_sel_hi:[1,0,1]
	ds_read_b128 v[62:65], v123
	ds_read_b128 v[66:69], v133
	v_pk_fma_f32 v[40:41], v[128:129], v[42:43], v[40:41] op_sel:[0,1,0]
	v_pk_fma_f32 v[42:43], v[126:127], v[46:47], v[190:191] op_sel_hi:[1,0,1]
	v_mov_b32_e32 v150, v3
	v_pk_fma_f32 v[42:43], v[128:129], v[46:47], v[42:43] op_sel:[0,1,0]
	s_waitcnt lgkmcnt(4)
	v_pk_fma_f32 v[46:47], v[126:127], v[50:51], v[192:193] op_sel_hi:[1,0,1]
	v_mov_b32_e32 v3, s33
	v_pk_fma_f32 v[46:47], v[128:129], v[50:51], v[46:47] op_sel:[0,1,0]
	v_mov_b32_e32 v50, v53
	v_pk_fma_f32 v[46:47], v[130:131], v[52:53], v[46:47] op_sel_hi:[1,0,1]
	s_waitcnt lgkmcnt(3)
	v_pk_fma_f32 v[52:53], v[126:127], v[54:55], v[194:195] op_sel_hi:[1,0,1]
	v_mov_b32_e32 v15, s34
	v_pk_fma_f32 v[52:53], v[128:129], v[54:55], v[52:53] op_sel:[0,1,0]
	s_waitcnt lgkmcnt(2)
	v_pk_fma_f32 v[54:55], v[126:127], v[58:59], v[196:197] op_sel_hi:[1,0,1]
	s_add_i32 s6, s3, 0xffff7000
	v_pk_fma_f32 v[54:55], v[128:129], v[58:59], v[54:55] op_sel:[0,1,0]
	s_waitcnt lgkmcnt(1)
	v_pk_fma_f32 v[58:59], v[126:127], v[62:63], v[198:199] op_sel_hi:[1,0,1]
	s_add_i32 s7, s3, 0xffff8000
	v_pk_fma_f32 v[58:59], v[128:129], v[62:63], v[58:59] op_sel:[0,1,0]
	s_waitcnt lgkmcnt(0)
; #define LAS __attribute__((address_space(3)))
; __device__ __forceinline__ void phase0(CArgs a, LAS unsigned char* lds, int tid, int lane, int wave, int G, int bx) {
;     ...
;                 for (int i = 0; i < 16; ++i) wv[i] = __builtin_nontemporal_load((const f32x2*)(wp + (size_t)i * NMOD));
; #pragma unroll
;                 for (int q = 0; q < 4; ++q) {
; #pragma unroll
;                     for (int r = 0; r < NB; ++r) { const f32x4 s4 = *(const LAS f32x4*)(S + r * 1024 + k + 4 * q);
;                         acc[r] += wv[4 * q] * s4[0]; acc[r] += wv[4 * q + 1] * s4[1]; acc[r] += wv[4 * q + 2] * s4[2]; acc[r] += wv[4 * q + 3] * s4[3]; } }
	v_pk_fma_f32 v[62:63], v[126:127], v[66:67], v[200:201] op_sel_hi:[1,0,1]
	v_pk_fma_f32 v[58:59], v[130:131], v[64:65], v[58:59] op_sel_hi:[1,0,1]
	v_pk_fma_f32 v[62:63], v[128:129], v[66:67], v[62:63] op_sel:[0,1,0]
	v_mov_b32_e32 v64, v69
	v_pk_fma_f32 v[62:63], v[130:131], v[68:69], v[62:63] op_sel_hi:[1,0,1]
	ds_read_b128 v[66:69], v3
	ds_read_b128 v[70:73], v15
	v_mov_b32_e32 v3, s6
	v_mov_b32_e32 v15, s7
	ds_read_b128 v[90:93], v3
	ds_read_b128 v[94:97], v15
	s_waitcnt lgkmcnt(3)
	v_pk_fma_f32 v[88:89], v[126:127], v[66:67], v[202:203] op_sel_hi:[1,0,1]
	s_add_i32 s6, s3, 0xffff9000
	v_pk_fma_f32 v[66:67], v[128:129], v[66:67], v[88:89] op_sel:[0,1,0]
	s_waitcnt lgkmcnt(2)
	v_pk_fma_f32 v[88:89], v[126:127], v[70:71], v[204:205] op_sel_hi:[1,0,1]
	s_add_i32 s7, s3, 0xffffa000
	v_mov_b32_e32 v3, s6
	v_pk_fma_f32 v[70:71], v[128:129], v[70:71], v[88:89] op_sel:[0,1,0]
	s_waitcnt lgkmcnt(1)
	v_pk_fma_f32 v[88:89], v[126:127], v[90:91], v[174:175] op_sel_hi:[1,0,1]
	v_mov_b32_e32 v15, s7
	ds_read_b128 v[98:101], v3
	ds_read_b128 v[102:105], v15
	v_pk_fma_f32 v[88:89], v[128:129], v[90:91], v[88:89] op_sel:[0,1,0]
	s_add_i32 s6, s3, 0xffffb000
	v_pk_fma_f32 v[90:91], v[130:131], v[92:93], v[88:89] op_sel_hi:[1,0,1]
	s_waitcnt lgkmcnt(2)
	v_pk_fma_f32 v[88:89], v[126:127], v[94:95], v[172:173] op_sel_hi:[1,0,1]
	s_add_i32 s7, s3, 0xffffc000
	v_pk_fma_f32 v[88:89], v[128:129], v[94:95], v[88:89] op_sel:[0,1,0]
	v_mov_b32_e32 v3, s6
	v_pk_fma_f32 v[94:95], v[130:131], v[96:97], v[88:89] op_sel_hi:[1,0,1]
	s_waitcnt lgkmcnt(1)
	v_pk_fma_f32 v[88:89], v[126:127], v[98:99], v[170:171] op_sel_hi:[1,0,1]
	v_mov_b32_e32 v15, s7
	ds_read_b128 v[106:109], v3
	ds_read_b128 v[110:113], v15
	v_pk_fma_f32 v[88:89], v[128:129], v[98:99], v[88:89] op_sel:[0,1,0]
	s_add_i32 s6, s3, 0xffffd000
	v_pk_fma_f32 v[98:99], v[130:131], v[100:101], v[88:89] op_sel_hi:[1,0,1]
	s_waitcnt lgkmcnt(2)
	v_pk_fma_f32 v[88:89], v[126:127], v[102:103], v[168:169] op_sel_hi:[1,0,1]
	s_add_i32 s7, s3, 0xffffe000
	v_pk_fma_f32 v[88:89], v[128:129], v[102:103], v[88:89] op_sel:[0,1,0]
	v_mov_b32_e32 v3, s6
	v_pk_fma_f32 v[102:103], v[130:131], v[104:105], v[88:89] op_sel_hi:[1,0,1]
	s_waitcnt lgkmcnt(1)
	v_pk_fma_f32 v[88:89], v[126:127], v[106:107], v[158:159] op_sel_hi:[1,0,1]
	v_mov_b32_e32 v15, s7
	ds_read_b128 v[114:117], v3
	ds_read_b128 v[118:121], v15
	v_pk_fma_f32 v[88:89], v[128:129], v[106:107], v[88:89] op_sel:[0,1,0]
	s_add_i32 s6, s3, 0xfffff000
	v_pk_fma_f32 v[106:107], v[130:131], v[108:109], v[88:89] op_sel_hi:[1,0,1]
	s_waitcnt lgkmcnt(2)
	v_pk_fma_f32 v[88:89], v[126:127], v[110:111], v[156:157] op_sel_hi:[1,0,1]
	v_mov_b32_e32 v15, s6
	v_pk_fma_f32 v[88:89], v[128:129], v[110:111], v[88:89] op_sel:[0,1,0]
	v_mov_b32_e32 v3, s3
	v_pk_fma_f32 v[110:111], v[130:131], v[112:113], v[88:89] op_sel_hi:[1,0,1]
	s_waitcnt lgkmcnt(1)
	v_pk_fma_f32 v[88:89], v[126:127], v[114:115], v[154:155] op_sel_hi:[1,0,1]
	v_pk_fma_f32 v[16:17], v[130:131], v[20:21], v[16:17] op_sel_hi:[1,0,1]
	v_pk_fma_f32 v[88:89], v[128:129], v[114:115], v[88:89] op_sel:[0,1,0]
	v_pk_fma_f32 v[18:19], v[130:131], v[24:25], v[18:19] op_sel_hi:[1,0,1]
	v_pk_fma_f32 v[114:115], v[130:131], v[116:117], v[88:89] op_sel_hi:[1,0,1]
	s_waitcnt lgkmcnt(0)
	v_pk_fma_f32 v[88:89], v[126:127], v[118:119], v[152:153] op_sel_hi:[1,0,1]
	ds_read_b128 v[152:155], v15
	ds_read_b128 v[156:159], v3
	v_pk_fma_f32 v[88:89], v[128:129], v[118:119], v[88:89] op_sel:[0,1,0]
	v_pk_fma_f32 v[28:29], v[130:131], v[32:33], v[28:29] op_sel_hi:[1,0,1]
	v_pk_fma_f32 v[118:119], v[130:131], v[120:121], v[88:89] op_sel_hi:[1,0,1]
	s_waitcnt lgkmcnt(1)
	v_pk_fma_f32 v[88:89], v[126:127], v[152:153], v[124:125] op_sel_hi:[1,0,1]
	s_waitcnt lgkmcnt(0)
	v_pk_fma_f32 v[86:87], v[126:127], v[156:157], v[86:87] op_sel_hi:[1,0,1]
	v_pk_fma_f32 v[88:89], v[128:129], v[152:153], v[88:89] op_sel:[0,1,0]
	v_pk_fma_f32 v[86:87], v[128:129], v[156:157], v[86:87] op_sel:[0,1,0]
	v_pk_fma_f32 v[30:31], v[130:131], v[36:37], v[30:31] op_sel_hi:[1,0,1]
	v_pk_fma_f32 v[40:41], v[130:131], v[44:45], v[40:41] op_sel_hi:[1,0,1]
	v_pk_fma_f32 v[42:43], v[130:131], v[48:49], v[42:43] op_sel_hi:[1,0,1]
	v_pk_fma_f32 v[52:53], v[130:131], v[56:57], v[52:53] op_sel_hi:[1,0,1]
	v_pk_fma_f32 v[54:55], v[130:131], v[60:61], v[54:55] op_sel_hi:[1,0,1]
	v_pk_fma_f32 v[66:67], v[130:131], v[68:69], v[66:67] op_sel_hi:[1,0,1]
	v_pk_fma_f32 v[70:71], v[130:131], v[72:73], v[70:71] op_sel_hi:[1,0,1]
	v_pk_fma_f32 v[122:123], v[130:131], v[154:155], v[88:89] op_sel_hi:[1,0,1]
	v_pk_fma_f32 v[126:127], v[130:131], v[158:159], v[86:87] op_sel_hi:[1,0,1]
	v_mov_b32_e32 v2, v21
	v_mov_b32_e32 v20, v25
	v_mov_b32_e32 v24, v33
	v_mov_b32_e32 v32, v37
	v_mov_b32_e32 v36, v45
	v_mov_b32_e32 v44, v49
	v_mov_b32_e32 v48, v57
	v_mov_b32_e32 v56, v61
	v_mov_b32_e32 v60, v65
	v_mov_b32_e32 v68, v69
	v_mov_b32_e32 v72, v73
	v_mov_b32_e32 v92, v93
	v_mov_b32_e32 v96, v97
	v_mov_b32_e32 v100, v101
	v_mov_b32_e32 v104, v105
	v_mov_b32_e32 v108, v109
	v_mov_b32_e32 v112, v113
	v_mov_b32_e32 v116, v117
	v_mov_b32_e32 v120, v121
	v_mov_b32_e32 v124, v155
	v_mov_b32_e32 v128, v159
	s_add_i32 s3, s3, 64
	s_mov_b64 s[6:7], 0xc0000
	v_lshl_add_u64 v[12:13], v[12:13], 0, s[6:7]
	s_cmpk_gt_u32 s2, 0x6f
	s_waitcnt vmcnt(0)
; #define LAS __attribute__((address_space(3)))
; __device__ __forceinline__ void phase0(CArgs a, LAS unsigned char* lds, int tid, int lane, int wave, int G, int bx) {
;     ...
;                 for (int i = 0; i < 16; ++i) wv[i] = __builtin_nontemporal_load((const f32x2*)(wp + (size_t)i * NMOD));
; #pragma unroll
;                 for (int q = 0; q < 4; ++q) {
; #pragma unroll
;                     for (int r = 0; r < NB; ++r) { const f32x4 s4 = *(const LAS f32x4*)(S + r * 1024 + k + 4 * q);
;                         acc[r] += wv[4 * q] * s4[0]; acc[r] += wv[4 * q + 1] * s4[1]; acc[r] += wv[4 * q + 2] * s4[2]; acc[r] += wv[4 * q + 3] * s4[3]; } }
;             }
;         }
;         __syncthreads();
; #pragma unroll
;         for (int r = 0; r < NB; ++r) *(LAS f32x2*)(S + (wave * NB + r) * 128 + lane * 2) = acc[r];
;         __syncthreads();
;         float* MOD = (float*)(ws + WS_MOD);
;         for (int idx = tid; idx < NB * 128; idx += 512) { const int r = idx >> 7, col = idx & 127; float s = a->in[11][l * NMOD + cb * 128 + col];
; #pragma unroll
;             for (int w = 0; w < 8; ++w) s += S[(w * NB + r) * 128 + col];
;             MOD[(size_t)(l * NB + r) * NMOD + cb * 128 + col] = s; }
	v_mov_b32_e32 v130, v250
	v_mov_b32_e32 v131, v251
	v_pk_fma_f32 v[88:89], v[130:131], v[74:75], v[76:77] op_sel_hi:[1,0,1]
	v_pk_fma_f32 v[86:87], v[130:131], v[80:81], v[78:79] op_sel_hi:[1,0,1]
	v_pk_fma_f32 v[84:85], v[130:131], v[84:85], v[82:83] op_sel_hi:[1,0,1]
	v_pk_fma_f32 v[82:83], v[130:131], v[132:133], v[134:135] op_sel_hi:[1,0,1]
	v_pk_fma_f32 v[80:81], v[130:131], v[138:139], v[136:137] op_sel_hi:[1,0,1]
	v_pk_fma_f32 v[78:79], v[130:131], v[144:145], v[140:141] op_sel_hi:[1,0,1]
	v_pk_fma_f32 v[76:77], v[130:131], v[142:143], v[146:147] op_sel_hi:[1,0,1]
	v_pk_fma_f32 v[74:75], v[130:131], v[150:151], v[148:149] op_sel_hi:[1,0,1]
	v_pk_fma_f32 v[152:153], v[130:131], v[14:15], v[0:1] op_sel_hi:[1,0,1]
	v_pk_fma_f32 v[150:151], v[130:131], v[2:3], v[16:17] op_sel_hi:[1,0,1]
	v_pk_fma_f32 v[148:149], v[130:131], v[20:21], v[18:19] op_sel_hi:[1,0,1]
	v_pk_fma_f32 v[146:147], v[130:131], v[26:27], v[22:23] op_sel_hi:[1,0,1]
	v_pk_fma_f32 v[144:145], v[130:131], v[24:25], v[28:29] op_sel_hi:[1,0,1]
	v_pk_fma_f32 v[142:143], v[130:131], v[32:33], v[30:31] op_sel_hi:[1,0,1]
	v_pk_fma_f32 v[140:141], v[130:131], v[38:39], v[34:35] op_sel_hi:[1,0,1]
	v_pk_fma_f32 v[134:135], v[130:131], v[36:37], v[40:41] op_sel_hi:[1,0,1]
	v_pk_fma_f32 v[2:3], v[130:131], v[44:45], v[42:43] op_sel_hi:[1,0,1]
	v_pk_fma_f32 v[0:1], v[130:131], v[50:51], v[46:47] op_sel_hi:[1,0,1]
	v_pk_fma_f32 v[138:139], v[130:131], v[48:49], v[52:53] op_sel_hi:[1,0,1]
	v_pk_fma_f32 v[136:137], v[130:131], v[56:57], v[54:55] op_sel_hi:[1,0,1]
	v_pk_fma_f32 v[132:133], v[130:131], v[60:61], v[58:59] op_sel_hi:[1,0,1]
	v_pk_fma_f32 v[40:41], v[130:131], v[64:65], v[62:63] op_sel_hi:[1,0,1]
	v_pk_fma_f32 v[38:39], v[130:131], v[68:69], v[66:67] op_sel_hi:[1,0,1]
	v_pk_fma_f32 v[36:37], v[130:131], v[72:73], v[70:71] op_sel_hi:[1,0,1]
	v_pk_fma_f32 v[32:33], v[130:131], v[92:93], v[90:91] op_sel_hi:[1,0,1]
	v_pk_fma_f32 v[30:31], v[130:131], v[96:97], v[94:95] op_sel_hi:[1,0,1]
	v_pk_fma_f32 v[28:29], v[130:131], v[100:101], v[98:99] op_sel_hi:[1,0,1]
	v_pk_fma_f32 v[26:27], v[130:131], v[104:105], v[102:103] op_sel_hi:[1,0,1]
	v_pk_fma_f32 v[24:25], v[130:131], v[108:109], v[106:107] op_sel_hi:[1,0,1]
	v_pk_fma_f32 v[22:23], v[130:131], v[112:113], v[110:111] op_sel_hi:[1,0,1]
	v_pk_fma_f32 v[20:21], v[130:131], v[116:117], v[114:115] op_sel_hi:[1,0,1]
	v_pk_fma_f32 v[18:19], v[130:131], v[120:121], v[118:119] op_sel_hi:[1,0,1]
	v_pk_fma_f32 v[16:17], v[130:131], v[124:125], v[122:123] op_sel_hi:[1,0,1]
	v_pk_fma_f32 v[14:15], v[130:131], v[128:129], v[126:127] op_sel_hi:[1,0,1]
	s_cbranch_scc0 .LBB0_843
	s_movk_i32 s14, 0x400
	s_mov_b64 s[6:7], 0
	s_and_b64 vcc, exec, s[4:5]
	s_cbranch_vccz .LBB0_835
	s_barrier
	ds_write2st64_b64 v5, v[88:89], v[86:87] offset1:1
	ds_write2st64_b64 v5, v[84:85], v[82:83] offset0:2 offset1:3
	ds_write2st64_b64 v5, v[80:81], v[78:79] offset0:4 offset1:5
	ds_write2st64_b64 v5, v[76:77], v[74:75] offset0:6 offset1:7
	ds_write2st64_b64 v5, v[152:153], v[150:151] offset0:8 offset1:9
	ds_write2st64_b64 v5, v[148:149], v[146:147] offset0:10 offset1:11
	ds_write2st64_b64 v5, v[144:145], v[142:143] offset0:12 offset1:13
	ds_write2st64_b64 v5, v[140:141], v[134:135] offset0:14 offset1:15
	ds_write2st64_b64 v5, v[2:3], v[0:1] offset0:16 offset1:17
	ds_write2st64_b64 v5, v[138:139], v[136:137] offset0:18 offset1:19
	ds_write2st64_b64 v5, v[132:133], v[40:41] offset0:20 offset1:21
	ds_write2st64_b64 v5, v[38:39], v[36:37] offset0:22 offset1:23
	ds_write2st64_b64 v5, v[32:33], v[30:31] offset0:24 offset1:25
	ds_write2st64_b64 v5, v[28:29], v[26:27] offset0:26 offset1:27
	ds_write2st64_b64 v5, v[24:25], v[22:23] offset0:28 offset1:29
	ds_write2st64_b64 v5, v[20:21], v[18:19] offset0:30 offset1:31
	ds_write2st64_b64 v5, v[16:17], v[14:15] offset0:32 offset1:33
	s_waitcnt lgkmcnt(0)
	s_barrier
	s_and_saveexec_b64 s[4:5], s[40:41]
	v_readlane_b32 s28, v254, 20
	s_mov_b64 s[30:31], 0x800
	v_readlane_b32 s29, v254, 21
	s_cbranch_execz .LBB0_833
	s_load_dwordx2 s[2:3], s[92:93], 0x58
	s_mul_i32 s6, s13, 0x3000
	s_add_i32 s6, s6, s0
	v_or_b32_e32 v0, s6, v165
	v_ashrrev_i32_e32 v1, 31, v0
	s_mul_i32 s13, s13, 34
	s_waitcnt lgkmcnt(0)
	v_lshl_add_u64 v[0:1], v[0:1], 2, s[2:3]
	v_lshl_add_u64 v[2:3], s[0:1], 2, v[6:7]
	s_mov_b64 s[0:1], 0
	v_mov_b32_e32 v10, v164
